# KV-finalise row loop: all rows of a wave requested up front (one memory latency instead of two per row), counted vmcnt per row; prompt-attention loops: dropped the mid-iteration vmcnt(0) that waited o
# baseline (speedup 1.0000x reference)
.LBB0_1968:
	s_or_b64 exec, exec, s[4:5]
	s_waitcnt lgkmcnt(0)
	v_mov_b32_e32 v0, 0
	s_barrier
	v_readlane_b32 s2, v255, 13
	v_mbcnt_lo_u32_b32 v0, -1, v0
	v_mbcnt_hi_u32_b32 v0, -1, v0
	v_add_u32_e32 v0, s33, v0
	s_mov_b32 s6, 0
	v_readfirstlane_b32 s1, v0
	s_ashr_i32 s1, s1, 6
	s_add_i32 s4, s1, s2
	v_mov_b32_e32 v1, 0
	s_cmpk_gt_i32 s4, 0x407f
	s_cbranch_scc1 .LBB0_1973
	s_ashr_i32 s7, s6, 31
	s_lshl_b64 s[6:7], s[6:7], 3
	v_readlane_b32 s8, v255, 2
	v_readlane_b32 s9, v255, 3
	s_add_u32 s6, s8, s6
	s_addc_u32 s7, s9, s7
	s_load_dwordx2 s[6:7], s[6:7], 0x80
	v_and_b32_e32 v2, 63, v0
	v_mov_b32_e32 v9, v1
	v_lshlrev_b32_e32 v8, 4, v2
	v_mov_b32_e32 v3, 0x500
	s_waitcnt lgkmcnt(0)
	v_lshl_add_u64 v[4:5], s[6:7], 0, v[8:9]
	v_lshlrev_b32_e32 v12, 3, v2
	v_mov_b32_e32 v13, v1
	v_mad_i64_i32 v[8:9], s[12:13], s4, v3, v[8:9]
	v_lshlrev_b32_e32 v0, 2, v2
	v_mad_i64_i32 v[6:7], s[8:9], s4, v3, v[12:13]
	s_mov_b64 s[12:13], 0x264f7300
	v_mov_b32_e32 v3, 0x280
	v_lshl_add_u64 v[8:9], v[8:9], 0, s[12:13]
	v_mad_i64_i32 v[10:11], s[12:13], s4, v3, v[0:1]
	s_mov_b64 s[12:13], 0x27947500
	s_nop 0
	v_lshl_add_u64 v[10:11], v[10:11], 0, s[12:13]
	v_mad_i64_i32 v[12:13], s[12:13], s4, v3, v[12:13]
	s_lshl_b32 s6, s0, 3
	s_lshl_b32 s2, s84, 8
	s_lshl_b32 s1, s1, 5
	s_ashr_i32 s5, s4, 31
	s_mov_b64 s[12:13], 0x27947300
	s_add_i32 s1, s2, s1
	s_lshl_b32 s2, s0, 8
	s_ashr_i32 s7, s6, 31
	v_lshl_add_u64 v[12:13], v[12:13], 0, s[12:13]
	s_lshl_b64 s[12:13], s[4:5], 7
	s_mov_b64 s[8:9], 0x264f7700
	s_add_u32 s11, s12, 0x34ff7300
	v_cmp_gt_u32_e32 vcc, 32, v2
	v_lshl_add_u64 v[6:7], v[6:7], 0, s[8:9]
	s_mul_i32 s8, s0, 0x2800
	s_mul_hi_i32 s9, s6, 0x500
	s_mul_i32 s14, s0, 0x1400
	s_mul_hi_i32 s15, s6, 0x280
	s_addc_u32 s22, s13, 0
	s_lshl_b64 s[16:17], s[6:7], 7
	v_mov_b32_e32 v3, 0x358637bd
	s_mov_b32 s23, 0x800000
	s_mov_b32 s24, 0x4080000
	v_lshlrev_b32_e32 v0, 2, v0
	s_mov_b32 s25, 0x5080000
	v_lshlrev_b32_e32 v14, 2, v2
	global_load_dwordx4 v[24:27], v[4:5], off
	v_readlane_b32 s46, v255, 9
	v_readlane_b32 s47, v255, 10
	s_and_b64 s[48:49], vcc, exec
	s_mov_b64 s[50:51], exec
	s_mov_b32 s34, s11
	s_mov_b32 s35, s22
	s_mov_b32 s36, s1
	s_mov_b32 s37, s4
	v_mov_b32_e32 v28, v8
	v_mov_b32_e32 v29, v9
	v_mov_b32_e32 v30, v6
	v_mov_b32_e32 v31, v7
	s_add_u32 s12, s82, s34
	s_addc_u32 s13, s83, s35
	global_load_dwordx4 v[60:63], v1, s[12:13]
	v_lshl_add_u64 v[32:33], s[82:83], 0, v[28:29]
	global_load_dwordx4 v[64:67], v[32:33], off
	s_and_b32 s26, s36, 0xffe0
	s_cmpk_lt_i32 s37, 0x4000
	s_cselect_b32 s20, s26, 0x10000
	v_or_b32_e32 v15, s20, v2
	v_lshlrev_b32_e32 v15, 3, v15
	v_lshl_add_u64 v[34:35], s[82:83], 0, v[30:31]
	s_mov_b64 exec, s[48:49]
	global_load_dwordx2 v[68:69], v15, s[46:47]
	global_load_dwordx2 v[70:71], v[34:35], off
	s_mov_b64 exec, s[50:51]
	s_add_i32 s38, s37, s6
	s_cmpk_lt_i32 s38, 0x4080
	s_cselect_b32 s40, s16, 0
	s_cselect_b32 s41, s17, 0
	s_cselect_b32 s42, s8, 0
	s_cselect_b32 s43, s9, 0
	s_cselect_b32 s44, s2, 0
	s_cselect_b32 s37, s38, s37
	s_add_u32 s34, s34, s40
	s_addc_u32 s35, s35, s41
	s_add_i32 s36, s36, s44
	v_lshl_add_u64 v[28:29], v[28:29], 0, s[42:43]
	v_lshl_add_u64 v[30:31], v[30:31], 0, s[42:43]
	s_add_u32 s12, s82, s34
	s_addc_u32 s13, s83, s35
	global_load_dwordx4 v[72:75], v1, s[12:13]
	v_lshl_add_u64 v[32:33], s[82:83], 0, v[28:29]
	global_load_dwordx4 v[76:79], v[32:33], off
	s_and_b32 s26, s36, 0xffe0
	s_cmpk_lt_i32 s37, 0x4000
	s_cselect_b32 s20, s26, 0x10000
	v_or_b32_e32 v15, s20, v2
	v_lshlrev_b32_e32 v15, 3, v15
	v_lshl_add_u64 v[34:35], s[82:83], 0, v[30:31]
	s_mov_b64 exec, s[48:49]
	global_load_dwordx2 v[80:81], v15, s[46:47]
	global_load_dwordx2 v[82:83], v[34:35], off
	s_mov_b64 exec, s[50:51]
	s_add_i32 s38, s37, s6
	s_cmpk_lt_i32 s38, 0x4080
	s_cselect_b32 s40, s16, 0
	s_cselect_b32 s41, s17, 0
	s_cselect_b32 s42, s8, 0
	s_cselect_b32 s43, s9, 0
	s_cselect_b32 s44, s2, 0
	s_cselect_b32 s37, s38, s37
	s_add_u32 s34, s34, s40
	s_addc_u32 s35, s35, s41
	s_add_i32 s36, s36, s44
	v_lshl_add_u64 v[28:29], v[28:29], 0, s[42:43]
	v_lshl_add_u64 v[30:31], v[30:31], 0, s[42:43]
	s_add_u32 s12, s82, s34
	s_addc_u32 s13, s83, s35
	global_load_dwordx4 v[84:87], v1, s[12:13]
	v_lshl_add_u64 v[32:33], s[82:83], 0, v[28:29]
	global_load_dwordx4 v[88:91], v[32:33], off
	s_and_b32 s26, s36, 0xffe0
	s_cmpk_lt_i32 s37, 0x4000
	s_cselect_b32 s20, s26, 0x10000
	v_or_b32_e32 v15, s20, v2
	v_lshlrev_b32_e32 v15, 3, v15
	v_lshl_add_u64 v[34:35], s[82:83], 0, v[30:31]
	s_mov_b64 exec, s[48:49]
	global_load_dwordx2 v[92:93], v15, s[46:47]
	global_load_dwordx2 v[94:95], v[34:35], off
	s_mov_b64 exec, s[50:51]
	s_add_i32 s38, s37, s6
	s_cmpk_lt_i32 s38, 0x4080
	s_cselect_b32 s40, s16, 0
	s_cselect_b32 s41, s17, 0
	s_cselect_b32 s42, s8, 0
	s_cselect_b32 s43, s9, 0
	s_cselect_b32 s44, s2, 0
	s_cselect_b32 s37, s38, s37
	s_add_u32 s34, s34, s40
	s_addc_u32 s35, s35, s41
	s_add_i32 s36, s36, s44
	v_lshl_add_u64 v[28:29], v[28:29], 0, s[42:43]
	v_lshl_add_u64 v[30:31], v[30:31], 0, s[42:43]
	s_add_u32 s12, s82, s34
	s_addc_u32 s13, s83, s35
	global_load_dwordx4 v[96:99], v1, s[12:13]
	v_lshl_add_u64 v[32:33], s[82:83], 0, v[28:29]
	global_load_dwordx4 v[100:103], v[32:33], off
	s_and_b32 s26, s36, 0xffe0
	s_cmpk_lt_i32 s37, 0x4000
	s_cselect_b32 s20, s26, 0x10000
	v_or_b32_e32 v15, s20, v2
	v_lshlrev_b32_e32 v15, 3, v15
	v_lshl_add_u64 v[34:35], s[82:83], 0, v[30:31]
	s_mov_b64 exec, s[48:49]
	global_load_dwordx2 v[104:105], v15, s[46:47]
	global_load_dwordx2 v[106:107], v[34:35], off
	s_mov_b64 exec, s[50:51]
	s_add_i32 s38, s37, s6
	s_cmpk_lt_i32 s38, 0x4080
	s_cselect_b32 s40, s16, 0
	s_cselect_b32 s41, s17, 0
	s_cselect_b32 s42, s8, 0
	s_cselect_b32 s43, s9, 0
	s_cselect_b32 s44, s2, 0
	s_cselect_b32 s37, s38, s37
	s_add_u32 s34, s34, s40
	s_addc_u32 s35, s35, s41
	s_add_i32 s36, s36, s44
	v_lshl_add_u64 v[28:29], v[28:29], 0, s[42:43]
	v_lshl_add_u64 v[30:31], v[30:31], 0, s[42:43]
	s_add_u32 s12, s82, s34
	s_addc_u32 s13, s83, s35
	global_load_dwordx4 v[108:111], v1, s[12:13]
	v_lshl_add_u64 v[32:33], s[82:83], 0, v[28:29]
	global_load_dwordx4 v[112:115], v[32:33], off
	s_and_b32 s26, s36, 0xffe0
	s_cmpk_lt_i32 s37, 0x4000
	s_cselect_b32 s20, s26, 0x10000
	v_or_b32_e32 v15, s20, v2
	v_lshlrev_b32_e32 v15, 3, v15
	v_lshl_add_u64 v[34:35], s[82:83], 0, v[30:31]
	s_mov_b64 exec, s[48:49]
	global_load_dwordx2 v[116:117], v15, s[46:47]
	global_load_dwordx2 v[118:119], v[34:35], off
	s_mov_b64 exec, s[50:51]
	s_add_i32 s38, s37, s6
	s_cmpk_lt_i32 s38, 0x4080
	s_cselect_b32 s40, s16, 0
	s_cselect_b32 s41, s17, 0
	s_cselect_b32 s42, s8, 0
	s_cselect_b32 s43, s9, 0
	s_cselect_b32 s44, s2, 0
	s_cselect_b32 s37, s38, s37
	s_add_u32 s34, s34, s40
	s_addc_u32 s35, s35, s41
	s_add_i32 s36, s36, s44
	v_lshl_add_u64 v[28:29], v[28:29], 0, s[42:43]
	v_lshl_add_u64 v[30:31], v[30:31], 0, s[42:43]
	s_add_u32 s12, s82, s34
	s_addc_u32 s13, s83, s35
	global_load_dwordx4 v[120:123], v1, s[12:13]
	v_lshl_add_u64 v[32:33], s[82:83], 0, v[28:29]
	global_load_dwordx4 v[124:127], v[32:33], off
	s_and_b32 s26, s36, 0xffe0
	s_cmpk_lt_i32 s37, 0x4000
	s_cselect_b32 s20, s26, 0x10000
	v_or_b32_e32 v15, s20, v2
	v_lshlrev_b32_e32 v15, 3, v15
	v_lshl_add_u64 v[34:35], s[82:83], 0, v[30:31]
	s_mov_b64 exec, s[48:49]
	global_load_dwordx2 v[128:129], v15, s[46:47]
	global_load_dwordx2 v[130:131], v[34:35], off
	s_mov_b64 exec, s[50:51]
	s_add_i32 s38, s37, s6
	s_cmpk_lt_i32 s38, 0x4080
	s_cselect_b32 s40, s16, 0
	s_cselect_b32 s41, s17, 0
	s_cselect_b32 s42, s8, 0
	s_cselect_b32 s43, s9, 0
	s_cselect_b32 s44, s2, 0
	s_cselect_b32 s37, s38, s37
	s_add_u32 s34, s34, s40
	s_addc_u32 s35, s35, s41
	s_add_i32 s36, s36, s44
	v_lshl_add_u64 v[28:29], v[28:29], 0, s[42:43]
	v_lshl_add_u64 v[30:31], v[30:31], 0, s[42:43]
	s_add_u32 s12, s82, s34
	s_addc_u32 s13, s83, s35
	global_load_dwordx4 v[132:135], v1, s[12:13]
	v_lshl_add_u64 v[32:33], s[82:83], 0, v[28:29]
	global_load_dwordx4 v[136:139], v[32:33], off
	s_and_b32 s26, s36, 0xffe0
	s_cmpk_lt_i32 s37, 0x4000
	s_cselect_b32 s20, s26, 0x10000
	v_or_b32_e32 v15, s20, v2
	v_lshlrev_b32_e32 v15, 3, v15
	v_lshl_add_u64 v[34:35], s[82:83], 0, v[30:31]
	s_mov_b64 exec, s[48:49]
	global_load_dwordx2 v[140:141], v15, s[46:47]
	global_load_dwordx2 v[142:143], v[34:35], off
	s_mov_b64 exec, s[50:51]
	s_add_i32 s38, s37, s6
	s_cmpk_lt_i32 s38, 0x4080
	s_cselect_b32 s40, s16, 0
	s_cselect_b32 s41, s17, 0
	s_cselect_b32 s42, s8, 0
	s_cselect_b32 s43, s9, 0
	s_cselect_b32 s44, s2, 0
	s_cselect_b32 s37, s38, s37
	s_add_u32 s34, s34, s40
	s_addc_u32 s35, s35, s41
	s_add_i32 s36, s36, s44
	v_lshl_add_u64 v[28:29], v[28:29], 0, s[42:43]
	v_lshl_add_u64 v[30:31], v[30:31], 0, s[42:43]
	s_add_u32 s12, s82, s34
	s_addc_u32 s13, s83, s35
	global_load_dwordx4 v[144:147], v1, s[12:13]
	v_lshl_add_u64 v[32:33], s[82:83], 0, v[28:29]
	global_load_dwordx4 v[148:151], v[32:33], off
	s_and_b32 s26, s36, 0xffe0
	s_cmpk_lt_i32 s37, 0x4000
	s_cselect_b32 s20, s26, 0x10000
	v_or_b32_e32 v15, s20, v2
	v_lshlrev_b32_e32 v15, 3, v15
	v_lshl_add_u64 v[34:35], s[82:83], 0, v[30:31]
	s_mov_b64 exec, s[48:49]
	global_load_dwordx2 v[152:153], v15, s[46:47]
	global_load_dwordx2 v[154:155], v[34:35], off
	s_mov_b64 exec, s[50:51]
	s_add_i32 s38, s37, s6
	s_cmpk_lt_i32 s38, 0x4080
	s_cselect_b32 s40, s16, 0
	s_cselect_b32 s41, s17, 0
	s_cselect_b32 s42, s8, 0
	s_cselect_b32 s43, s9, 0
	s_cselect_b32 s44, s2, 0
	s_cselect_b32 s37, s38, s37
	s_add_u32 s34, s34, s40
	s_addc_u32 s35, s35, s41
	s_add_i32 s36, s36, s44
	v_lshl_add_u64 v[28:29], v[28:29], 0, s[42:43]
	v_lshl_add_u64 v[30:31], v[30:31], 0, s[42:43]
	s_add_u32 s12, s82, s34
	s_addc_u32 s13, s83, s35
	global_load_dwordx4 v[156:159], v1, s[12:13]
	v_lshl_add_u64 v[32:33], s[82:83], 0, v[28:29]
	global_load_dwordx4 v[160:163], v[32:33], off
	s_and_b32 s26, s36, 0xffe0
	s_cmpk_lt_i32 s37, 0x4000
	s_cselect_b32 s20, s26, 0x10000
	v_or_b32_e32 v15, s20, v2
	v_lshlrev_b32_e32 v15, 3, v15
	v_lshl_add_u64 v[34:35], s[82:83], 0, v[30:31]
	s_mov_b64 exec, s[48:49]
	global_load_dwordx2 v[164:165], v15, s[46:47]
	global_load_dwordx2 v[166:167], v[34:35], off
	s_mov_b64 exec, s[50:51]
	s_add_i32 s18, s4, 0xffffc000
	s_cmpk_lt_i32 s4, 0x4000
	s_cselect_b32 s12, s24, 0x5480000
	s_cselect_b32 s19, s5, 0
	s_cselect_b32 s18, s4, s18
	s_add_u32 s28, s80, s12
	s_addc_u32 s29, s81, 0
	s_lshl_b64 s[26:27], s[18:19], 10
	s_add_u32 s26, s28, s26
	s_addc_u32 s27, s29, s27
	s_waitcnt vmcnt(32)
	v_mov_b32_e32 v16, v60
	v_mov_b32_e32 v17, v63
	v_mov_b32_e32 v28, v61
	v_mov_b32_e32 v29, v62
	v_pk_add_f32 v[16:17], v[28:29], v[16:17]
	s_nop 0
	v_add_f32_e32 v15, v16, v17
	v_fmamk_f32 v15, v15, 0x3b800000, v3
	v_mul_f32_e32 v16, 0x4b800000, v15
	v_cmp_gt_f32_e64 s[12:13], s23, v15
	s_nop 1
	v_cndmask_b32_e64 v15, v15, v16, s[12:13]
	v_rsq_f32_e32 v15, v15
	s_nop 0
	v_mul_f32_e32 v16, 0x45800000, v15
	v_cndmask_b32_e64 v16, v15, v16, s[12:13]
	v_pk_mul_f32 v[20:21], v[64:65], v[16:17] op_sel_hi:[1,0]
	v_pk_mul_f32 v[16:17], v[66:67], v[16:17] op_sel_hi:[1,0]
	v_pk_mul_f32 v[18:19], v[26:27], v[16:17]
	v_pk_mul_f32 v[16:17], v[24:25], v[20:21]
	global_store_dwordx4 v0, v[16:19], s[26:27]
	s_nop 1
	v_cvt_pk_bf16_f32 v16, v16, v17
	v_cvt_pk_bf16_f32 v17, v18, v19
	v_lshl_add_u64 v[18:19], s[82:83], 0, v[12:13]
	global_store_dwordx2 v[18:19], v[16:17], off
	s_cmpk_lt_i32 s4, 0x4000
	s_cselect_b32 s20, s25, 0x54a0000
	s_add_u32 s20, s80, s20
	s_addc_u32 s21, s81, 0
	s_lshl_b64 s[18:19], s[18:19], 8
	s_add_u32 s18, s20, s18
	s_addc_u32 s19, s21, s19
	s_mov_b64 exec, s[48:49]
	v_pk_mul_f32 v[20:21], v[70:71], v[68:69]
	v_pk_mul_f32 v[16:17], v[70:71], v[68:69] op_sel:[1,0] op_sel_hi:[0,1]
	v_sub_f32_e32 v15, v20, v21
	v_add_f32_e32 v16, v16, v17
	global_store_dword v14, v15, s[18:19]
	global_store_dword v14, v16, s[18:19] offset:128
	v_cvt_pk_bf16_f32 v15, v15, v16
	v_lshl_add_u64 v[16:17], s[82:83], 0, v[10:11]
	global_store_dword v[16:17], v15, off
	s_mov_b64 exec, s[50:51]
	s_add_u32 s4, s4, s6
	s_addc_u32 s5, s5, s7
	s_add_i32 s1, s1, s2
	s_add_u32 s11, s11, s16
	s_addc_u32 s22, s22, s17
	v_lshl_add_u64 v[6:7], v[6:7], 0, s[8:9]
	v_lshl_add_u64 v[8:9], v[8:9], 0, s[8:9]
	v_lshl_add_u64 v[10:11], v[10:11], 0, s[14:15]
	v_lshl_add_u64 v[12:13], v[12:13], 0, s[14:15]
	s_cmpk_lt_i32 s4, 0x4080
	s_cbranch_scc0 .Lmy_kvf_done
	s_add_i32 s18, s4, 0xffffc000
	s_cmpk_lt_i32 s4, 0x4000
	s_cselect_b32 s12, s24, 0x5480000
	s_cselect_b32 s19, s5, 0
	s_cselect_b32 s18, s4, s18
	s_add_u32 s28, s80, s12
	s_addc_u32 s29, s81, 0
	s_lshl_b64 s[26:27], s[18:19], 10
	s_add_u32 s26, s28, s26
	s_addc_u32 s27, s29, s27
	s_waitcnt vmcnt(33)
	v_mov_b32_e32 v16, v72
	v_mov_b32_e32 v17, v75
	v_mov_b32_e32 v28, v73
	v_mov_b32_e32 v29, v74
	v_pk_add_f32 v[16:17], v[28:29], v[16:17]
	s_nop 0
	v_add_f32_e32 v15, v16, v17
	v_fmamk_f32 v15, v15, 0x3b800000, v3
	v_mul_f32_e32 v16, 0x4b800000, v15
	v_cmp_gt_f32_e64 s[12:13], s23, v15
	s_nop 1
	v_cndmask_b32_e64 v15, v15, v16, s[12:13]
	v_rsq_f32_e32 v15, v15
	s_nop 0
	v_mul_f32_e32 v16, 0x45800000, v15
	v_cndmask_b32_e64 v16, v15, v16, s[12:13]
	v_pk_mul_f32 v[20:21], v[76:77], v[16:17] op_sel_hi:[1,0]
	v_pk_mul_f32 v[16:17], v[78:79], v[16:17] op_sel_hi:[1,0]
	v_pk_mul_f32 v[18:19], v[26:27], v[16:17]
	v_pk_mul_f32 v[16:17], v[24:25], v[20:21]
	global_store_dwordx4 v0, v[16:19], s[26:27]
	s_nop 1
	v_cvt_pk_bf16_f32 v16, v16, v17
	v_cvt_pk_bf16_f32 v17, v18, v19
	v_lshl_add_u64 v[18:19], s[82:83], 0, v[12:13]
	global_store_dwordx2 v[18:19], v[16:17], off
	s_cmpk_lt_i32 s4, 0x4000
	s_cselect_b32 s20, s25, 0x54a0000
	s_add_u32 s20, s80, s20
	s_addc_u32 s21, s81, 0
	s_lshl_b64 s[18:19], s[18:19], 8
	s_add_u32 s18, s20, s18
	s_addc_u32 s19, s21, s19
	s_mov_b64 exec, s[48:49]
	v_pk_mul_f32 v[20:21], v[82:83], v[80:81]
	v_pk_mul_f32 v[16:17], v[82:83], v[80:81] op_sel:[1,0] op_sel_hi:[0,1]
	v_sub_f32_e32 v15, v20, v21
	v_add_f32_e32 v16, v16, v17
	global_store_dword v14, v15, s[18:19]
	global_store_dword v14, v16, s[18:19] offset:128
	v_cvt_pk_bf16_f32 v15, v15, v16
	v_lshl_add_u64 v[16:17], s[82:83], 0, v[10:11]
	global_store_dword v[16:17], v15, off
	s_mov_b64 exec, s[50:51]
	s_add_u32 s4, s4, s6
	s_addc_u32 s5, s5, s7
	s_add_i32 s1, s1, s2
	s_add_u32 s11, s11, s16
	s_addc_u32 s22, s22, s17
	v_lshl_add_u64 v[6:7], v[6:7], 0, s[8:9]
	v_lshl_add_u64 v[8:9], v[8:9], 0, s[8:9]
	v_lshl_add_u64 v[10:11], v[10:11], 0, s[14:15]
	v_lshl_add_u64 v[12:13], v[12:13], 0, s[14:15]
	s_cmpk_lt_i32 s4, 0x4080
	s_cbranch_scc0 .Lmy_kvf_done
	s_add_i32 s18, s4, 0xffffc000
	s_cmpk_lt_i32 s4, 0x4000
	s_cselect_b32 s12, s24, 0x5480000
	s_cselect_b32 s19, s5, 0
	s_cselect_b32 s18, s4, s18
	s_add_u32 s28, s80, s12
	s_addc_u32 s29, s81, 0
	s_lshl_b64 s[26:27], s[18:19], 10
	s_add_u32 s26, s28, s26
	s_addc_u32 s27, s29, s27
	s_waitcnt vmcnt(34)
	v_mov_b32_e32 v16, v84
	v_mov_b32_e32 v17, v87
	v_mov_b32_e32 v28, v85
	v_mov_b32_e32 v29, v86
	v_pk_add_f32 v[16:17], v[28:29], v[16:17]
	s_nop 0
	v_add_f32_e32 v15, v16, v17
	v_fmamk_f32 v15, v15, 0x3b800000, v3
	v_mul_f32_e32 v16, 0x4b800000, v15
	v_cmp_gt_f32_e64 s[12:13], s23, v15
	s_nop 1
	v_cndmask_b32_e64 v15, v15, v16, s[12:13]
	v_rsq_f32_e32 v15, v15
	s_nop 0
	v_mul_f32_e32 v16, 0x45800000, v15
	v_cndmask_b32_e64 v16, v15, v16, s[12:13]
	v_pk_mul_f32 v[20:21], v[88:89], v[16:17] op_sel_hi:[1,0]
	v_pk_mul_f32 v[16:17], v[90:91], v[16:17] op_sel_hi:[1,0]
	v_pk_mul_f32 v[18:19], v[26:27], v[16:17]
	v_pk_mul_f32 v[16:17], v[24:25], v[20:21]
	global_store_dwordx4 v0, v[16:19], s[26:27]
	s_nop 1
	v_cvt_pk_bf16_f32 v16, v16, v17
	v_cvt_pk_bf16_f32 v17, v18, v19
	v_lshl_add_u64 v[18:19], s[82:83], 0, v[12:13]
	global_store_dwordx2 v[18:19], v[16:17], off
	s_cmpk_lt_i32 s4, 0x4000
	s_cselect_b32 s20, s25, 0x54a0000
	s_add_u32 s20, s80, s20
	s_addc_u32 s21, s81, 0
	s_lshl_b64 s[18:19], s[18:19], 8
	s_add_u32 s18, s20, s18
	s_addc_u32 s19, s21, s19
	s_mov_b64 exec, s[48:49]
	v_pk_mul_f32 v[20:21], v[94:95], v[92:93]
	v_pk_mul_f32 v[16:17], v[94:95], v[92:93] op_sel:[1,0] op_sel_hi:[0,1]
	v_sub_f32_e32 v15, v20, v21
	v_add_f32_e32 v16, v16, v17
	global_store_dword v14, v15, s[18:19]
	global_store_dword v14, v16, s[18:19] offset:128
	v_cvt_pk_bf16_f32 v15, v15, v16
	v_lshl_add_u64 v[16:17], s[82:83], 0, v[10:11]
	global_store_dword v[16:17], v15, off
	s_mov_b64 exec, s[50:51]
	s_add_u32 s4, s4, s6
	s_addc_u32 s5, s5, s7
	s_add_i32 s1, s1, s2
	s_add_u32 s11, s11, s16
	s_addc_u32 s22, s22, s17
	v_lshl_add_u64 v[6:7], v[6:7], 0, s[8:9]
	v_lshl_add_u64 v[8:9], v[8:9], 0, s[8:9]
	v_lshl_add_u64 v[10:11], v[10:11], 0, s[14:15]
	v_lshl_add_u64 v[12:13], v[12:13], 0, s[14:15]
	s_cmpk_lt_i32 s4, 0x4080
	s_cbranch_scc0 .Lmy_kvf_done
	s_add_i32 s18, s4, 0xffffc000
	s_cmpk_lt_i32 s4, 0x4000
	s_cselect_b32 s12, s24, 0x5480000
	s_cselect_b32 s19, s5, 0
	s_cselect_b32 s18, s4, s18
	s_add_u32 s28, s80, s12
	s_addc_u32 s29, s81, 0
	s_lshl_b64 s[26:27], s[18:19], 10
	s_add_u32 s26, s28, s26
	s_addc_u32 s27, s29, s27
	s_waitcnt vmcnt(35)
	v_mov_b32_e32 v16, v96
	v_mov_b32_e32 v17, v99
	v_mov_b32_e32 v28, v97
	v_mov_b32_e32 v29, v98
	v_pk_add_f32 v[16:17], v[28:29], v[16:17]
	s_nop 0
	v_add_f32_e32 v15, v16, v17
	v_fmamk_f32 v15, v15, 0x3b800000, v3
	v_mul_f32_e32 v16, 0x4b800000, v15
	v_cmp_gt_f32_e64 s[12:13], s23, v15
	s_nop 1
	v_cndmask_b32_e64 v15, v15, v16, s[12:13]
	v_rsq_f32_e32 v15, v15
	s_nop 0
	v_mul_f32_e32 v16, 0x45800000, v15
	v_cndmask_b32_e64 v16, v15, v16, s[12:13]
	v_pk_mul_f32 v[20:21], v[100:101], v[16:17] op_sel_hi:[1,0]
	v_pk_mul_f32 v[16:17], v[102:103], v[16:17] op_sel_hi:[1,0]
	v_pk_mul_f32 v[18:19], v[26:27], v[16:17]
	v_pk_mul_f32 v[16:17], v[24:25], v[20:21]
	global_store_dwordx4 v0, v[16:19], s[26:27]
	s_nop 1
	v_cvt_pk_bf16_f32 v16, v16, v17
	v_cvt_pk_bf16_f32 v17, v18, v19
	v_lshl_add_u64 v[18:19], s[82:83], 0, v[12:13]
	global_store_dwordx2 v[18:19], v[16:17], off
	s_cmpk_lt_i32 s4, 0x4000
	s_cselect_b32 s20, s25, 0x54a0000
	s_add_u32 s20, s80, s20
	s_addc_u32 s21, s81, 0
	s_lshl_b64 s[18:19], s[18:19], 8
	s_add_u32 s18, s20, s18
	s_addc_u32 s19, s21, s19
	s_mov_b64 exec, s[48:49]
	v_pk_mul_f32 v[20:21], v[106:107], v[104:105]
	v_pk_mul_f32 v[16:17], v[106:107], v[104:105] op_sel:[1,0] op_sel_hi:[0,1]
	v_sub_f32_e32 v15, v20, v21
	v_add_f32_e32 v16, v16, v17
	global_store_dword v14, v15, s[18:19]
	global_store_dword v14, v16, s[18:19] offset:128
	v_cvt_pk_bf16_f32 v15, v15, v16
	v_lshl_add_u64 v[16:17], s[82:83], 0, v[10:11]
	global_store_dword v[16:17], v15, off
	s_mov_b64 exec, s[50:51]
	s_add_u32 s4, s4, s6
	s_addc_u32 s5, s5, s7
	s_add_i32 s1, s1, s2
	s_add_u32 s11, s11, s16
	s_addc_u32 s22, s22, s17
	v_lshl_add_u64 v[6:7], v[6:7], 0, s[8:9]
	v_lshl_add_u64 v[8:9], v[8:9], 0, s[8:9]
	v_lshl_add_u64 v[10:11], v[10:11], 0, s[14:15]
	v_lshl_add_u64 v[12:13], v[12:13], 0, s[14:15]
	s_cmpk_lt_i32 s4, 0x4080
	s_cbranch_scc0 .Lmy_kvf_done
	s_add_i32 s18, s4, 0xffffc000
	s_cmpk_lt_i32 s4, 0x4000
	s_cselect_b32 s12, s24, 0x5480000
	s_cselect_b32 s19, s5, 0
	s_cselect_b32 s18, s4, s18
	s_add_u32 s28, s80, s12
	s_addc_u32 s29, s81, 0
	s_lshl_b64 s[26:27], s[18:19], 10
	s_add_u32 s26, s28, s26
	s_addc_u32 s27, s29, s27
	s_waitcnt vmcnt(36)
	v_mov_b32_e32 v16, v108
	v_mov_b32_e32 v17, v111
	v_mov_b32_e32 v28, v109
	v_mov_b32_e32 v29, v110
	v_pk_add_f32 v[16:17], v[28:29], v[16:17]
	s_nop 0
	v_add_f32_e32 v15, v16, v17
	v_fmamk_f32 v15, v15, 0x3b800000, v3
	v_mul_f32_e32 v16, 0x4b800000, v15
	v_cmp_gt_f32_e64 s[12:13], s23, v15
	s_nop 1
	v_cndmask_b32_e64 v15, v15, v16, s[12:13]
	v_rsq_f32_e32 v15, v15
	s_nop 0
	v_mul_f32_e32 v16, 0x45800000, v15
	v_cndmask_b32_e64 v16, v15, v16, s[12:13]
	v_pk_mul_f32 v[20:21], v[112:113], v[16:17] op_sel_hi:[1,0]
	v_pk_mul_f32 v[16:17], v[114:115], v[16:17] op_sel_hi:[1,0]
	v_pk_mul_f32 v[18:19], v[26:27], v[16:17]
	v_pk_mul_f32 v[16:17], v[24:25], v[20:21]
	global_store_dwordx4 v0, v[16:19], s[26:27]
	s_nop 1
	v_cvt_pk_bf16_f32 v16, v16, v17
	v_cvt_pk_bf16_f32 v17, v18, v19
	v_lshl_add_u64 v[18:19], s[82:83], 0, v[12:13]
	global_store_dwordx2 v[18:19], v[16:17], off
	s_cmpk_lt_i32 s4, 0x4000
	s_cselect_b32 s20, s25, 0x54a0000
	s_add_u32 s20, s80, s20
	s_addc_u32 s21, s81, 0
	s_lshl_b64 s[18:19], s[18:19], 8
	s_add_u32 s18, s20, s18
	s_addc_u32 s19, s21, s19
	s_mov_b64 exec, s[48:49]
	v_pk_mul_f32 v[20:21], v[118:119], v[116:117]
	v_pk_mul_f32 v[16:17], v[118:119], v[116:117] op_sel:[1,0] op_sel_hi:[0,1]
	v_sub_f32_e32 v15, v20, v21
	v_add_f32_e32 v16, v16, v17
	global_store_dword v14, v15, s[18:19]
	global_store_dword v14, v16, s[18:19] offset:128
	v_cvt_pk_bf16_f32 v15, v15, v16
	v_lshl_add_u64 v[16:17], s[82:83], 0, v[10:11]
	global_store_dword v[16:17], v15, off
	s_mov_b64 exec, s[50:51]
	s_add_u32 s4, s4, s6
	s_addc_u32 s5, s5, s7
	s_add_i32 s1, s1, s2
	s_add_u32 s11, s11, s16
	s_addc_u32 s22, s22, s17
	v_lshl_add_u64 v[6:7], v[6:7], 0, s[8:9]
	v_lshl_add_u64 v[8:9], v[8:9], 0, s[8:9]
	v_lshl_add_u64 v[10:11], v[10:11], 0, s[14:15]
	v_lshl_add_u64 v[12:13], v[12:13], 0, s[14:15]
	s_cmpk_lt_i32 s4, 0x4080
	s_cbranch_scc0 .Lmy_kvf_done
	s_add_i32 s18, s4, 0xffffc000
	s_cmpk_lt_i32 s4, 0x4000
	s_cselect_b32 s12, s24, 0x5480000
	s_cselect_b32 s19, s5, 0
	s_cselect_b32 s18, s4, s18
	s_add_u32 s28, s80, s12
	s_addc_u32 s29, s81, 0
	s_lshl_b64 s[26:27], s[18:19], 10
	s_add_u32 s26, s28, s26
	s_addc_u32 s27, s29, s27
	s_waitcnt vmcnt(37)
	v_mov_b32_e32 v16, v120
	v_mov_b32_e32 v17, v123
	v_mov_b32_e32 v28, v121
	v_mov_b32_e32 v29, v122
	v_pk_add_f32 v[16:17], v[28:29], v[16:17]
	s_nop 0
	v_add_f32_e32 v15, v16, v17
	v_fmamk_f32 v15, v15, 0x3b800000, v3
	v_mul_f32_e32 v16, 0x4b800000, v15
	v_cmp_gt_f32_e64 s[12:13], s23, v15
	s_nop 1
	v_cndmask_b32_e64 v15, v15, v16, s[12:13]
	v_rsq_f32_e32 v15, v15
	s_nop 0
	v_mul_f32_e32 v16, 0x45800000, v15
	v_cndmask_b32_e64 v16, v15, v16, s[12:13]
	v_pk_mul_f32 v[20:21], v[124:125], v[16:17] op_sel_hi:[1,0]
	v_pk_mul_f32 v[16:17], v[126:127], v[16:17] op_sel_hi:[1,0]
	v_pk_mul_f32 v[18:19], v[26:27], v[16:17]
	v_pk_mul_f32 v[16:17], v[24:25], v[20:21]
	global_store_dwordx4 v0, v[16:19], s[26:27]
	s_nop 1
	v_cvt_pk_bf16_f32 v16, v16, v17
	v_cvt_pk_bf16_f32 v17, v18, v19
	v_lshl_add_u64 v[18:19], s[82:83], 0, v[12:13]
	global_store_dwordx2 v[18:19], v[16:17], off
	s_cmpk_lt_i32 s4, 0x4000
	s_cselect_b32 s20, s25, 0x54a0000
	s_add_u32 s20, s80, s20
	s_addc_u32 s21, s81, 0
	s_lshl_b64 s[18:19], s[18:19], 8
	s_add_u32 s18, s20, s18
	s_addc_u32 s19, s21, s19
	s_mov_b64 exec, s[48:49]
	v_pk_mul_f32 v[20:21], v[130:131], v[128:129]
	v_pk_mul_f32 v[16:17], v[130:131], v[128:129] op_sel:[1,0] op_sel_hi:[0,1]
	v_sub_f32_e32 v15, v20, v21
	v_add_f32_e32 v16, v16, v17
	global_store_dword v14, v15, s[18:19]
	global_store_dword v14, v16, s[18:19] offset:128
	v_cvt_pk_bf16_f32 v15, v15, v16
	v_lshl_add_u64 v[16:17], s[82:83], 0, v[10:11]
	global_store_dword v[16:17], v15, off
	s_mov_b64 exec, s[50:51]
	s_add_u32 s4, s4, s6
	s_addc_u32 s5, s5, s7
	s_add_i32 s1, s1, s2
	s_add_u32 s11, s11, s16
	s_addc_u32 s22, s22, s17
	v_lshl_add_u64 v[6:7], v[6:7], 0, s[8:9]
	v_lshl_add_u64 v[8:9], v[8:9], 0, s[8:9]
	v_lshl_add_u64 v[10:11], v[10:11], 0, s[14:15]
	v_lshl_add_u64 v[12:13], v[12:13], 0, s[14:15]
	s_cmpk_lt_i32 s4, 0x4080
	s_cbranch_scc0 .Lmy_kvf_done
	s_add_i32 s18, s4, 0xffffc000
	s_cmpk_lt_i32 s4, 0x4000
	s_cselect_b32 s12, s24, 0x5480000
	s_cselect_b32 s19, s5, 0
	s_cselect_b32 s18, s4, s18
	s_add_u32 s28, s80, s12
	s_addc_u32 s29, s81, 0
	s_lshl_b64 s[26:27], s[18:19], 10
	s_add_u32 s26, s28, s26
	s_addc_u32 s27, s29, s27
	s_waitcnt vmcnt(38)
	v_mov_b32_e32 v16, v132
	v_mov_b32_e32 v17, v135
	v_mov_b32_e32 v28, v133
	v_mov_b32_e32 v29, v134
	v_pk_add_f32 v[16:17], v[28:29], v[16:17]
	s_nop 0
	v_add_f32_e32 v15, v16, v17
	v_fmamk_f32 v15, v15, 0x3b800000, v3
	v_mul_f32_e32 v16, 0x4b800000, v15
	v_cmp_gt_f32_e64 s[12:13], s23, v15
	s_nop 1
	v_cndmask_b32_e64 v15, v15, v16, s[12:13]
	v_rsq_f32_e32 v15, v15
	s_nop 0
	v_mul_f32_e32 v16, 0x45800000, v15
	v_cndmask_b32_e64 v16, v15, v16, s[12:13]
	v_pk_mul_f32 v[20:21], v[136:137], v[16:17] op_sel_hi:[1,0]
	v_pk_mul_f32 v[16:17], v[138:139], v[16:17] op_sel_hi:[1,0]
	v_pk_mul_f32 v[18:19], v[26:27], v[16:17]
	v_pk_mul_f32 v[16:17], v[24:25], v[20:21]
	global_store_dwordx4 v0, v[16:19], s[26:27]
	s_nop 1
	v_cvt_pk_bf16_f32 v16, v16, v17
	v_cvt_pk_bf16_f32 v17, v18, v19
	v_lshl_add_u64 v[18:19], s[82:83], 0, v[12:13]
	global_store_dwordx2 v[18:19], v[16:17], off
	s_cmpk_lt_i32 s4, 0x4000
	s_cselect_b32 s20, s25, 0x54a0000
	s_add_u32 s20, s80, s20
	s_addc_u32 s21, s81, 0
	s_lshl_b64 s[18:19], s[18:19], 8
	s_add_u32 s18, s20, s18
	s_addc_u32 s19, s21, s19
	s_mov_b64 exec, s[48:49]
	v_pk_mul_f32 v[20:21], v[142:143], v[140:141]
	v_pk_mul_f32 v[16:17], v[142:143], v[140:141] op_sel:[1,0] op_sel_hi:[0,1]
	v_sub_f32_e32 v15, v20, v21
	v_add_f32_e32 v16, v16, v17
	global_store_dword v14, v15, s[18:19]
	global_store_dword v14, v16, s[18:19] offset:128
	v_cvt_pk_bf16_f32 v15, v15, v16
	v_lshl_add_u64 v[16:17], s[82:83], 0, v[10:11]
	global_store_dword v[16:17], v15, off
	s_mov_b64 exec, s[50:51]
	s_add_u32 s4, s4, s6
	s_addc_u32 s5, s5, s7
	s_add_i32 s1, s1, s2
	s_add_u32 s11, s11, s16
	s_addc_u32 s22, s22, s17
	v_lshl_add_u64 v[6:7], v[6:7], 0, s[8:9]
	v_lshl_add_u64 v[8:9], v[8:9], 0, s[8:9]
	v_lshl_add_u64 v[10:11], v[10:11], 0, s[14:15]
	v_lshl_add_u64 v[12:13], v[12:13], 0, s[14:15]
	s_cmpk_lt_i32 s4, 0x4080
	s_cbranch_scc0 .Lmy_kvf_done
	s_add_i32 s18, s4, 0xffffc000
	s_cmpk_lt_i32 s4, 0x4000
	s_cselect_b32 s12, s24, 0x5480000
	s_cselect_b32 s19, s5, 0
	s_cselect_b32 s18, s4, s18
	s_add_u32 s28, s80, s12
	s_addc_u32 s29, s81, 0
	s_lshl_b64 s[26:27], s[18:19], 10
	s_add_u32 s26, s28, s26
	s_addc_u32 s27, s29, s27
	s_waitcnt vmcnt(39)
	v_mov_b32_e32 v16, v144
	v_mov_b32_e32 v17, v147
	v_mov_b32_e32 v28, v145
	v_mov_b32_e32 v29, v146
	v_pk_add_f32 v[16:17], v[28:29], v[16:17]
	s_nop 0
	v_add_f32_e32 v15, v16, v17
	v_fmamk_f32 v15, v15, 0x3b800000, v3
	v_mul_f32_e32 v16, 0x4b800000, v15
	v_cmp_gt_f32_e64 s[12:13], s23, v15
	s_nop 1
	v_cndmask_b32_e64 v15, v15, v16, s[12:13]
	v_rsq_f32_e32 v15, v15
	s_nop 0
	v_mul_f32_e32 v16, 0x45800000, v15
	v_cndmask_b32_e64 v16, v15, v16, s[12:13]
	v_pk_mul_f32 v[20:21], v[148:149], v[16:17] op_sel_hi:[1,0]
	v_pk_mul_f32 v[16:17], v[150:151], v[16:17] op_sel_hi:[1,0]
	v_pk_mul_f32 v[18:19], v[26:27], v[16:17]
	v_pk_mul_f32 v[16:17], v[24:25], v[20:21]
	global_store_dwordx4 v0, v[16:19], s[26:27]
	s_nop 1
	v_cvt_pk_bf16_f32 v16, v16, v17
	v_cvt_pk_bf16_f32 v17, v18, v19
	v_lshl_add_u64 v[18:19], s[82:83], 0, v[12:13]
	global_store_dwordx2 v[18:19], v[16:17], off
	s_cmpk_lt_i32 s4, 0x4000
	s_cselect_b32 s20, s25, 0x54a0000
	s_add_u32 s20, s80, s20
	s_addc_u32 s21, s81, 0
	s_lshl_b64 s[18:19], s[18:19], 8
	s_add_u32 s18, s20, s18
	s_addc_u32 s19, s21, s19
	s_mov_b64 exec, s[48:49]
	v_pk_mul_f32 v[20:21], v[154:155], v[152:153]
	v_pk_mul_f32 v[16:17], v[154:155], v[152:153] op_sel:[1,0] op_sel_hi:[0,1]
	v_sub_f32_e32 v15, v20, v21
	v_add_f32_e32 v16, v16, v17
	global_store_dword v14, v15, s[18:19]
	global_store_dword v14, v16, s[18:19] offset:128
	v_cvt_pk_bf16_f32 v15, v15, v16
	v_lshl_add_u64 v[16:17], s[82:83], 0, v[10:11]
	global_store_dword v[16:17], v15, off
	s_mov_b64 exec, s[50:51]
	s_add_u32 s4, s4, s6
	s_addc_u32 s5, s5, s7
	s_add_i32 s1, s1, s2
	s_add_u32 s11, s11, s16
	s_addc_u32 s22, s22, s17
	v_lshl_add_u64 v[6:7], v[6:7], 0, s[8:9]
	v_lshl_add_u64 v[8:9], v[8:9], 0, s[8:9]
	v_lshl_add_u64 v[10:11], v[10:11], 0, s[14:15]
	v_lshl_add_u64 v[12:13], v[12:13], 0, s[14:15]
	s_cmpk_lt_i32 s4, 0x4080
	s_cbranch_scc0 .Lmy_kvf_done
	s_add_i32 s18, s4, 0xffffc000
	s_cmpk_lt_i32 s4, 0x4000
	s_cselect_b32 s12, s24, 0x5480000
	s_cselect_b32 s19, s5, 0
	s_cselect_b32 s18, s4, s18
	s_add_u32 s28, s80, s12
	s_addc_u32 s29, s81, 0
	s_lshl_b64 s[26:27], s[18:19], 10
	s_add_u32 s26, s28, s26
	s_addc_u32 s27, s29, s27
	s_waitcnt vmcnt(40)
	v_mov_b32_e32 v16, v156
	v_mov_b32_e32 v17, v159
	v_mov_b32_e32 v28, v157
	v_mov_b32_e32 v29, v158
	v_pk_add_f32 v[16:17], v[28:29], v[16:17]
	s_nop 0
	v_add_f32_e32 v15, v16, v17
	v_fmamk_f32 v15, v15, 0x3b800000, v3
	v_mul_f32_e32 v16, 0x4b800000, v15
	v_cmp_gt_f32_e64 s[12:13], s23, v15
	s_nop 1
	v_cndmask_b32_e64 v15, v15, v16, s[12:13]
	v_rsq_f32_e32 v15, v15
	s_nop 0
	v_mul_f32_e32 v16, 0x45800000, v15
	v_cndmask_b32_e64 v16, v15, v16, s[12:13]
	v_pk_mul_f32 v[20:21], v[160:161], v[16:17] op_sel_hi:[1,0]
	v_pk_mul_f32 v[16:17], v[162:163], v[16:17] op_sel_hi:[1,0]
	v_pk_mul_f32 v[18:19], v[26:27], v[16:17]
	v_pk_mul_f32 v[16:17], v[24:25], v[20:21]
	global_store_dwordx4 v0, v[16:19], s[26:27]
	s_nop 1
	v_cvt_pk_bf16_f32 v16, v16, v17
	v_cvt_pk_bf16_f32 v17, v18, v19
	v_lshl_add_u64 v[18:19], s[82:83], 0, v[12:13]
	global_store_dwordx2 v[18:19], v[16:17], off
	s_cmpk_lt_i32 s4, 0x4000
	s_cselect_b32 s20, s25, 0x54a0000
	s_add_u32 s20, s80, s20
	s_addc_u32 s21, s81, 0
	s_lshl_b64 s[18:19], s[18:19], 8
	s_add_u32 s18, s20, s18
	s_addc_u32 s19, s21, s19
	s_mov_b64 exec, s[48:49]
	v_pk_mul_f32 v[20:21], v[166:167], v[164:165]
	v_pk_mul_f32 v[16:17], v[166:167], v[164:165] op_sel:[1,0] op_sel_hi:[0,1]
	v_sub_f32_e32 v15, v20, v21
	v_add_f32_e32 v16, v16, v17
	global_store_dword v14, v15, s[18:19]
	global_store_dword v14, v16, s[18:19] offset:128
	v_cvt_pk_bf16_f32 v15, v15, v16
	v_lshl_add_u64 v[16:17], s[82:83], 0, v[10:11]
	global_store_dword v[16:17], v15, off
	s_mov_b64 exec, s[50:51]
	s_add_u32 s4, s4, s6
	s_addc_u32 s5, s5, s7
	s_add_i32 s1, s1, s2
	s_add_u32 s11, s11, s16
	s_addc_u32 s22, s22, s17
	v_lshl_add_u64 v[6:7], v[6:7], 0, s[8:9]
	v_lshl_add_u64 v[8:9], v[8:9], 0, s[8:9]
	v_lshl_add_u64 v[10:11], v[10:11], 0, s[14:15]
	v_lshl_add_u64 v[12:13], v[12:13], 0, s[14:15]
	s_cmpk_lt_i32 s4, 0x4080
	s_cbranch_scc0 .Lmy_kvf_done
	s_waitcnt vmcnt(0)
	s_branch .LBB0_1971
.Lmy_kvf_done:
	s_waitcnt vmcnt(0)
	s_branch .LBB0_1973

.LBB0_2371:
	v_sub_f32_e32 v0, v80, v233
	v_exp_f32_e32 v236, v0
	v_sub_f32_e32 v0, v81, v233
	v_exp_f32_e32 v237, v0
	v_sub_f32_e32 v0, v82, v233
	v_exp_f32_e32 v82, v0
	v_sub_f32_e32 v0, v83, v233
	v_exp_f32_e32 v0, v0
	v_add_f32_e32 v83, v236, v237
	v_pk_add_f32 v[80:81], v[82:83], v[0:1]
	s_nop 0
	v_pk_add_f32 v[234:235], v[80:81], v[80:81] op_sel_hi:[0,1]
	v_sub_f32_e32 v80, v84, v233
	v_exp_f32_e32 v238, v80
	v_sub_f32_e32 v80, v85, v233
	v_exp_f32_e32 v239, v80
	v_sub_f32_e32 v80, v86, v233
	v_exp_f32_e32 v84, v80
	v_sub_f32_e32 v80, v87, v233
	v_exp_f32_e32 v234, v80
	v_add_f32_e32 v85, v238, v239
	v_cvt_pk_bf16_f32 v80, v236, v237
	v_cvt_pk_bf16_f32 v81, v82, v0
	v_pk_add_f32 v[82:83], v[84:85], v[234:235]
	v_sub_f32_e32 v0, v88, v233
	v_pk_add_f32 v[86:87], v[82:83], v[82:83] op_sel_hi:[0,1]
	v_sub_f32_e32 v82, v89, v233
	v_exp_f32_e32 v235, v82
	v_sub_f32_e32 v82, v90, v233
	v_exp_f32_e32 v0, v0
	v_exp_f32_e32 v88, v82
	v_sub_f32_e32 v82, v91, v233
	v_exp_f32_e32 v86, v82
	v_add_f32_e32 v89, v0, v235
	v_cvt_pk_bf16_f32 v82, v238, v239
	v_cvt_pk_bf16_f32 v83, v84, v234
	v_pk_add_f32 v[84:85], v[88:89], v[86:87]
	s_nop 0
	v_pk_add_f32 v[238:239], v[84:85], v[84:85] op_sel_hi:[0,1]
	v_sub_f32_e32 v84, v92, v233
	v_exp_f32_e32 v241, v84
	v_sub_f32_e32 v84, v93, v233
	v_exp_f32_e32 v242, v84
	v_sub_f32_e32 v84, v94, v233
	v_exp_f32_e32 v240, v84
	v_sub_f32_e32 v84, v95, v233
	v_exp_f32_e32 v238, v84
	v_cvt_pk_bf16_f32 v84, v0, v235
	v_cvt_pk_bf16_f32 v85, v88, v86
	v_cvt_pk_bf16_f32 v86, v241, v242
	v_cvt_pk_bf16_f32 v87, v240, v238
	ds_read_b64_tr_b16 v[88:89], v179 offset:49152
	ds_read_b64_tr_b16 v[90:91], v180 offset:49152
	ds_read_b64_tr_b16 v[92:93], v181 offset:49152
	ds_read_b64_tr_b16 v[94:95], v182 offset:49152
	ds_read_b64_tr_b16 v[234:235], v183 offset:49152
	ds_read_b64_tr_b16 v[236:237], v184 offset:49152
	v_add_f32_e32 v241, v241, v242
	v_pk_add_f32 v[238:239], v[240:241], v[238:239]
	s_nop 0
	v_add_f32_e32 v0, v238, v239
	v_add_f32_e32 v169, v169, v0
	s_setprio 1
	s_waitcnt lgkmcnt(4)
	v_mfma_f32_32x32x16_bf16 v[64:79], v[88:91], v[80:83], v[64:79]
	ds_read_b64_tr_b16 v[238:239], v223 offset:49152
	ds_read_b64_tr_b16 v[240:241], v185 offset:49152
	s_waitcnt lgkmcnt(4)
	v_mfma_f32_32x32x16_bf16 v[48:63], v[92:95], v[80:83], v[48:63]
	ds_read_b64_tr_b16 v[88:89], v186 offset:49152
	ds_read_b64_tr_b16 v[90:91], v224 offset:55296
	s_waitcnt lgkmcnt(4)
	v_mfma_f32_32x32x16_bf16 v[32:47], v[234:237], v[80:83], v[32:47]
	ds_read_b64_tr_b16 v[92:93], v187 offset:49152
	ds_read_b64_tr_b16 v[94:95], v225 offset:55296
	s_waitcnt lgkmcnt(4)
	v_mfma_f32_32x32x16_bf16 v[16:31], v[238:241], v[80:83], v[16:31]
	ds_read_b64_tr_b16 v[234:235], v188 offset:49152
	ds_read_b64_tr_b16 v[236:237], v226 offset:55296
	s_waitcnt lgkmcnt(4)
	v_mfma_f32_32x32x16_bf16 v[64:79], v[88:91], v[84:87], v[64:79]
	ds_read_b64_tr_b16 v[80:81], v189 offset:49152
	ds_read_b64_tr_b16 v[82:83], v227 offset:55296
	s_waitcnt lgkmcnt(4)
	v_mfma_f32_32x32x16_bf16 v[48:63], v[92:95], v[84:87], v[48:63]
	s_waitcnt lgkmcnt(2)
	v_mfma_f32_32x32x16_bf16 v[32:47], v[234:237], v[84:87], v[32:47]
	s_waitcnt lgkmcnt(0)
	v_mfma_f32_32x32x16_bf16 v[16:31], v[80:83], v[84:87], v[16:31]
	s_setprio 0
	s_sub_i32 s70, s89, 64
	s_cmp_gt_i32 s70, s88
	s_cbranch_scc1 .LBB0_2377
	v_add_u32_e32 v0, v170, v152
	v_add_u32_e32 v84, v170, v153
	ds_read_b128 v[80:83], v0
	ds_read_b128 v[234:237], v84
	v_add_u32_e32 v0, v170, v154
	v_add_u32_e32 v84, v170, v155
	ds_read_b128 v[238:241], v0
	ds_read_b128 v[242:245], v84
	s_add_i32 s70, s47, s89
	s_setprio 1
	s_waitcnt lgkmcnt(3)
	v_mfma_f32_32x32x16_bf16 v[80:95], v[80:83], v[140:143], 0
	v_add_u32_e32 v0, v170, v156
	ds_read_b128 v[246:249], v0
	s_waitcnt lgkmcnt(3)
	v_mfma_f32_32x32x16_bf16 v[80:95], v[234:237], v[136:139], v[80:95]
	v_add_u32_e32 v0, v170, v157
	ds_read_b128 v[250:253], v0
	s_waitcnt lgkmcnt(3)
	v_mfma_f32_32x32x16_bf16 v[80:95], v[238:241], v[132:135], v[80:95]
	v_add_u32_e32 v0, v170, v163
	ds_read_b128 v[234:237], v0
	s_waitcnt lgkmcnt(3)
	v_mfma_f32_32x32x16_bf16 v[80:95], v[242:245], v[128:131], v[80:95]
	v_add_u32_e32 v0, v170, v164
	ds_read_b128 v[238:241], v0
	s_waitcnt lgkmcnt(3)
	v_mfma_f32_32x32x16_bf16 v[80:95], v[246:249], v[124:127], v[80:95]
	v_add_u32_e32 v0, v170, v165
	ds_read_b128 v[242:245], v0
	s_waitcnt lgkmcnt(3)
	v_mfma_f32_32x32x16_bf16 v[80:95], v[250:253], v[120:123], v[80:95]
	v_add_u32_e32 v0, v170, v166
	ds_read_b128 v[246:249], v0
	s_waitcnt lgkmcnt(3)
	v_mfma_f32_32x32x16_bf16 v[80:95], v[234:237], v[116:119], v[80:95]
	v_add_u32_e32 v0, v170, v167
	ds_read_b128 v[250:253], v0
	s_waitcnt lgkmcnt(3)
	v_mfma_f32_32x32x16_bf16 v[80:95], v[238:241], v[112:115], v[80:95]
	v_add_u32_e32 v0, v170, v168
	ds_read_b128 v[234:237], v0
	s_waitcnt lgkmcnt(3)
	v_mfma_f32_32x32x16_bf16 v[80:95], v[242:245], v[108:111], v[80:95]
	s_waitcnt lgkmcnt(2)
	v_mfma_f32_32x32x16_bf16 v[80:95], v[246:249], v[104:107], v[80:95]
	s_waitcnt lgkmcnt(1)
	v_mfma_f32_32x32x16_bf16 v[80:95], v[250:253], v[100:103], v[80:95]
	s_waitcnt lgkmcnt(0)
	v_mfma_f32_32x32x16_bf16 v[80:95], v[234:237], v[96:99], v[80:95]
	s_setprio 0
	s_cmpk_lg_i32 s70, 0x60
	s_cbranch_scc1 .LBB0_2374
	s_nop 8
	v_cndmask_b32_e64 v0, v80, v160, s[8:9]
	v_cndmask_b32_e64 v81, v160, v81, s[12:13]
	v_cndmask_b32_e64 v80, v0, v80, s[12:13]
	v_cndmask_b32_e64 v82, v82, v160, s[14:15]
	v_cndmask_b32_e64 v83, v83, v160, s[16:17]
	v_cndmask_b32_e64 v84, v84, v160, s[18:19]
	v_cndmask_b32_e64 v85, v85, v160, s[20:21]
	v_cndmask_b32_e64 v86, v86, v160, s[22:23]
	v_cndmask_b32_e64 v87, v87, v160, s[24:25]
	v_cndmask_b32_e64 v88, v88, v160, s[26:27]
	v_cndmask_b32_e64 v89, v89, v160, s[28:29]
	v_cndmask_b32_e64 v90, v90, v160, s[30:31]
	v_cndmask_b32_e64 v91, v91, v160, s[34:35]
	v_cndmask_b32_e64 v92, v92, v160, s[36:37]
	v_cndmask_b32_e64 v93, v93, v160, s[38:39]
	v_cndmask_b32_e64 v94, v94, v160, s[40:41]
	v_cndmask_b32_e64 v95, v95, v160, s[42:43]

.LBB0_2384:
	v_sub_f32_e32 v0, v80, v233
	v_exp_f32_e32 v9, v0
	v_sub_f32_e32 v0, v81, v233
	v_exp_f32_e32 v10, v0
	v_sub_f32_e32 v0, v82, v233
	v_exp_f32_e32 v4, v0
	v_sub_f32_e32 v0, v83, v233
	v_exp_f32_e32 v0, v0
	v_add_f32_e32 v5, v9, v10
	v_pk_add_f32 v[2:3], v[4:5], v[0:1]
	s_nop 0
	v_pk_add_f32 v[6:7], v[2:3], v[2:3] op_sel_hi:[0,1]
	v_sub_f32_e32 v2, v84, v233
	v_exp_f32_e32 v13, v2
	v_sub_f32_e32 v2, v85, v233
	v_exp_f32_e32 v14, v2
	v_sub_f32_e32 v2, v86, v233
	v_exp_f32_e32 v8, v2
	v_sub_f32_e32 v2, v87, v233
	v_exp_f32_e32 v6, v2
	v_cvt_pk_bf16_f32 v2, v9, v10
	v_add_f32_e32 v9, v13, v14
	v_cvt_pk_bf16_f32 v3, v4, v0
	v_pk_add_f32 v[4:5], v[8:9], v[6:7]
	v_sub_f32_e32 v0, v88, v233
	v_pk_add_f32 v[10:11], v[4:5], v[4:5] op_sel_hi:[0,1]
	v_sub_f32_e32 v4, v89, v233
	v_exp_f32_e32 v9, v4
	v_sub_f32_e32 v4, v90, v233
	v_exp_f32_e32 v0, v0
	v_exp_f32_e32 v12, v4
	v_sub_f32_e32 v4, v91, v233
	v_exp_f32_e32 v10, v4
	v_cvt_pk_bf16_f32 v4, v13, v14
	v_add_f32_e32 v13, v0, v9
	v_cvt_pk_bf16_f32 v5, v8, v6
	v_pk_add_f32 v[6:7], v[12:13], v[10:11]
	s_nop 0
	v_pk_add_f32 v[14:15], v[6:7], v[6:7] op_sel_hi:[0,1]
	v_sub_f32_e32 v6, v92, v233
	v_exp_f32_e32 v89, v6
	v_sub_f32_e32 v6, v93, v233
	v_exp_f32_e32 v90, v6
	v_sub_f32_e32 v6, v94, v233
	v_exp_f32_e32 v88, v6
	v_sub_f32_e32 v6, v95, v233
	v_exp_f32_e32 v14, v6
	v_cvt_pk_bf16_f32 v6, v0, v9
	v_cvt_pk_bf16_f32 v7, v12, v10
	v_cvt_pk_bf16_f32 v8, v89, v90
	v_cvt_pk_bf16_f32 v9, v88, v14
	ds_read_b64_tr_b16 v[10:11], v201
	ds_read_b64_tr_b16 v[12:13], v202
	ds_read_b64_tr_b16 v[80:81], v203
	ds_read_b64_tr_b16 v[82:83], v204
	ds_read_b64_tr_b16 v[84:85], v205
	ds_read_b64_tr_b16 v[86:87], v206
	v_add_f32_e32 v89, v89, v90
	v_pk_add_f32 v[14:15], v[88:89], v[14:15]
	s_nop 0
	v_add_f32_e32 v0, v14, v15
	v_add_f32_e32 v169, v169, v0
	s_setprio 1
	s_waitcnt lgkmcnt(4)
	v_mfma_f32_32x32x16_bf16 v[64:79], v[10:13], v[2:5], v[64:79]
	ds_read_b64_tr_b16 v[88:89], v228
	ds_read_b64_tr_b16 v[90:91], v207
	s_waitcnt lgkmcnt(4)
	v_mfma_f32_32x32x16_bf16 v[48:63], v[80:83], v[2:5], v[48:63]
	ds_read_b64_tr_b16 v[10:11], v208
	ds_read_b64_tr_b16 v[12:13], v229 offset:6144
	s_waitcnt lgkmcnt(4)
	v_mfma_f32_32x32x16_bf16 v[32:47], v[84:87], v[2:5], v[32:47]
	ds_read_b64_tr_b16 v[80:81], v209
	ds_read_b64_tr_b16 v[82:83], v230 offset:6144
	s_waitcnt lgkmcnt(4)
	v_mfma_f32_32x32x16_bf16 v[16:31], v[88:91], v[2:5], v[16:31]
	ds_read_b64_tr_b16 v[84:85], v210
	ds_read_b64_tr_b16 v[86:87], v231 offset:6144
	s_waitcnt lgkmcnt(4)
	v_mfma_f32_32x32x16_bf16 v[64:79], v[10:13], v[6:9], v[64:79]
	ds_read_b64_tr_b16 v[2:3], v211
	ds_read_b64_tr_b16 v[4:5], v232 offset:6144
	s_waitcnt lgkmcnt(4)
	v_mfma_f32_32x32x16_bf16 v[48:63], v[80:83], v[6:9], v[48:63]
	s_waitcnt lgkmcnt(2)
	v_mfma_f32_32x32x16_bf16 v[32:47], v[84:87], v[6:9], v[32:47]
	s_waitcnt lgkmcnt(0)
	v_mfma_f32_32x32x16_bf16 v[16:31], v[2:5], v[6:9], v[16:31]
	s_setprio 0
	s_cmp_gt_i32 s89, s88
	s_cbranch_scc1 .LBB0_2363
	v_add_u32_e32 v0, v170, v152
	v_add_u32_e32 v6, v170, v153
	ds_read_b128 v[2:5], v0 offset:24576
	ds_read_b128 v[6:9], v6 offset:24576
	v_add_u32_e32 v0, v170, v154
	v_add_u32_e32 v14, v170, v155
	ds_read_b128 v[10:13], v0 offset:24576
	ds_read_b128 v[234:237], v14 offset:24576
	s_setprio 1
	s_waitcnt lgkmcnt(3)
	v_mfma_f32_32x32x16_bf16 v[80:95], v[2:5], v[140:143], 0
	v_add_u32_e32 v0, v170, v156
	ds_read_b128 v[238:241], v0 offset:24576
	s_waitcnt lgkmcnt(3)
	v_mfma_f32_32x32x16_bf16 v[80:95], v[6:9], v[136:139], v[80:95]
	v_add_u32_e32 v0, v170, v157
	ds_read_b128 v[2:5], v0 offset:24576
	s_waitcnt lgkmcnt(3)
	v_mfma_f32_32x32x16_bf16 v[80:95], v[10:13], v[132:135], v[80:95]
	v_add_u32_e32 v0, v170, v163
	ds_read_b128 v[6:9], v0 offset:24576
	s_waitcnt lgkmcnt(3)
	v_mfma_f32_32x32x16_bf16 v[80:95], v[234:237], v[128:131], v[80:95]
	v_add_u32_e32 v0, v170, v164
	ds_read_b128 v[10:13], v0 offset:24576
	s_waitcnt lgkmcnt(3)
	v_mfma_f32_32x32x16_bf16 v[80:95], v[238:241], v[124:127], v[80:95]
	v_add_u32_e32 v0, v170, v165
	ds_read_b128 v[234:237], v0 offset:24576
	s_waitcnt lgkmcnt(3)
	v_mfma_f32_32x32x16_bf16 v[80:95], v[2:5], v[120:123], v[80:95]
	v_add_u32_e32 v0, v170, v166
	ds_read_b128 v[238:241], v0 offset:24576
	s_waitcnt lgkmcnt(3)
	v_mfma_f32_32x32x16_bf16 v[80:95], v[6:9], v[116:119], v[80:95]
	v_add_u32_e32 v0, v170, v167
	ds_read_b128 v[2:5], v0 offset:24576
	s_waitcnt lgkmcnt(3)
	v_mfma_f32_32x32x16_bf16 v[80:95], v[10:13], v[112:115], v[80:95]
	v_add_u32_e32 v0, v170, v168
	ds_read_b128 v[6:9], v0 offset:24576
	s_waitcnt lgkmcnt(3)
	v_mfma_f32_32x32x16_bf16 v[80:95], v[234:237], v[108:111], v[80:95]
	s_waitcnt lgkmcnt(2)
	v_mfma_f32_32x32x16_bf16 v[80:95], v[238:241], v[104:107], v[80:95]
	s_waitcnt lgkmcnt(1)
	v_mfma_f32_32x32x16_bf16 v[80:95], v[2:5], v[100:103], v[80:95]
	s_waitcnt lgkmcnt(0)
	v_mfma_f32_32x32x16_bf16 v[80:95], v[6:9], v[96:99], v[80:95]
	s_setprio 0
	s_cmp_lg_u32 s1, 0
	s_cbranch_scc1 .LBB0_2387
	s_nop 8
	v_cndmask_b32_e64 v0, v80, v160, s[8:9]
	v_cndmask_b32_e64 v81, v160, v81, s[12:13]
	v_cndmask_b32_e64 v80, v0, v80, s[12:13]
	v_cndmask_b32_e64 v82, v82, v160, s[14:15]
	v_cndmask_b32_e64 v83, v83, v160, s[16:17]
	v_cndmask_b32_e64 v84, v84, v160, s[18:19]
	v_cndmask_b32_e64 v85, v85, v160, s[20:21]
	v_cndmask_b32_e64 v86, v86, v160, s[22:23]
	v_cndmask_b32_e64 v87, v87, v160, s[24:25]
	v_cndmask_b32_e64 v88, v88, v160, s[26:27]
	v_cndmask_b32_e64 v89, v89, v160, s[28:29]
	v_cndmask_b32_e64 v90, v90, v160, s[30:31]
	v_cndmask_b32_e64 v91, v91, v160, s[34:35]
	v_cndmask_b32_e64 v92, v92, v160, s[36:37]
	v_cndmask_b32_e64 v93, v93, v160, s[38:39]
	v_cndmask_b32_e64 v94, v94, v160, s[40:41]
	v_cndmask_b32_e64 v95, v95, v160, s[42:43]

.LBB0_2423:
	v_sub_f32_e32 v0, v80, v231
	v_exp_f32_e32 v234, v0
	v_sub_f32_e32 v0, v81, v231
	v_exp_f32_e32 v235, v0
	v_sub_f32_e32 v0, v82, v231
	v_exp_f32_e32 v82, v0
	v_sub_f32_e32 v0, v83, v231
	v_exp_f32_e32 v0, v0
	v_add_f32_e32 v83, v234, v235
	v_pk_add_f32 v[80:81], v[82:83], v[0:1]
	s_nop 0
	v_pk_add_f32 v[232:233], v[80:81], v[80:81] op_sel_hi:[0,1]
	v_sub_f32_e32 v80, v84, v231
	v_exp_f32_e32 v236, v80
	v_sub_f32_e32 v80, v85, v231
	v_exp_f32_e32 v237, v80
	v_sub_f32_e32 v80, v86, v231
	v_exp_f32_e32 v84, v80
	v_sub_f32_e32 v80, v87, v231
	v_exp_f32_e32 v232, v80
	v_add_f32_e32 v85, v236, v237
	v_cvt_pk_bf16_f32 v80, v234, v235
	v_cvt_pk_bf16_f32 v81, v82, v0
	v_pk_add_f32 v[82:83], v[84:85], v[232:233]
	v_sub_f32_e32 v0, v88, v231
	v_pk_add_f32 v[86:87], v[82:83], v[82:83] op_sel_hi:[0,1]
	v_sub_f32_e32 v82, v89, v231
	v_exp_f32_e32 v233, v82
	v_sub_f32_e32 v82, v90, v231
	v_exp_f32_e32 v0, v0
	v_exp_f32_e32 v88, v82
	v_sub_f32_e32 v82, v91, v231
	v_exp_f32_e32 v86, v82
	v_add_f32_e32 v89, v0, v233
	v_cvt_pk_bf16_f32 v82, v236, v237
	v_cvt_pk_bf16_f32 v83, v84, v232
	v_pk_add_f32 v[84:85], v[88:89], v[86:87]
	s_nop 0
	v_pk_add_f32 v[236:237], v[84:85], v[84:85] op_sel_hi:[0,1]
	v_sub_f32_e32 v84, v92, v231
	v_exp_f32_e32 v239, v84
	v_sub_f32_e32 v84, v93, v231
	v_exp_f32_e32 v240, v84
	v_sub_f32_e32 v84, v94, v231
	v_exp_f32_e32 v238, v84
	v_sub_f32_e32 v84, v95, v231
	v_exp_f32_e32 v236, v84
	v_cvt_pk_bf16_f32 v84, v0, v233
	v_cvt_pk_bf16_f32 v85, v88, v86
	v_cvt_pk_bf16_f32 v86, v239, v240
	v_cvt_pk_bf16_f32 v87, v238, v236
	ds_read_b64_tr_b16 v[88:89], v177 offset:49152
	ds_read_b64_tr_b16 v[90:91], v178 offset:49152
	ds_read_b64_tr_b16 v[92:93], v179 offset:49152
	ds_read_b64_tr_b16 v[94:95], v180 offset:49152
	ds_read_b64_tr_b16 v[232:233], v181 offset:49152
	ds_read_b64_tr_b16 v[234:235], v182 offset:49152
	v_add_f32_e32 v239, v239, v240
	v_pk_add_f32 v[236:237], v[238:239], v[236:237]
	s_nop 0
	v_add_f32_e32 v0, v236, v237
	v_add_f32_e32 v168, v168, v0
	s_setprio 1
	s_waitcnt lgkmcnt(4)
	v_mfma_f32_32x32x16_bf16 v[64:79], v[88:91], v[80:83], v[64:79]
	ds_read_b64_tr_b16 v[236:237], v221 offset:49152
	ds_read_b64_tr_b16 v[238:239], v183 offset:49152
	s_waitcnt lgkmcnt(4)
	v_mfma_f32_32x32x16_bf16 v[48:63], v[92:95], v[80:83], v[48:63]
	ds_read_b64_tr_b16 v[88:89], v184 offset:49152
	ds_read_b64_tr_b16 v[90:91], v222 offset:55296
	s_waitcnt lgkmcnt(4)
	v_mfma_f32_32x32x16_bf16 v[32:47], v[232:235], v[80:83], v[32:47]
	ds_read_b64_tr_b16 v[92:93], v185 offset:49152
	ds_read_b64_tr_b16 v[94:95], v223 offset:55296
	s_waitcnt lgkmcnt(4)
	v_mfma_f32_32x32x16_bf16 v[16:31], v[236:239], v[80:83], v[16:31]
	ds_read_b64_tr_b16 v[232:233], v186 offset:49152
	ds_read_b64_tr_b16 v[234:235], v224 offset:55296
	s_waitcnt lgkmcnt(4)
	v_mfma_f32_32x32x16_bf16 v[64:79], v[88:91], v[84:87], v[64:79]
	ds_read_b64_tr_b16 v[80:81], v187 offset:49152
	ds_read_b64_tr_b16 v[82:83], v225 offset:55296
	s_waitcnt lgkmcnt(4)
	v_mfma_f32_32x32x16_bf16 v[48:63], v[92:95], v[84:87], v[48:63]
	s_waitcnt lgkmcnt(2)
	v_mfma_f32_32x32x16_bf16 v[32:47], v[232:235], v[84:87], v[32:47]
	s_waitcnt lgkmcnt(0)
	v_mfma_f32_32x32x16_bf16 v[16:31], v[80:83], v[84:87], v[16:31]
	s_setprio 0
	s_sub_i32 s58, s72, 64
	s_cmp_gt_i32 s58, s71
	s_cbranch_scc1 .LBB0_2429
	v_add_u32_e32 v0, v167, v155
	v_add_u32_e32 v84, v167, v156
	ds_read_b128 v[80:83], v0
	ds_read_b128 v[232:235], v84
	v_add_u32_e32 v0, v167, v157
	v_add_u32_e32 v84, v167, v158
	ds_read_b128 v[236:239], v0
	ds_read_b128 v[240:243], v84
	s_add_i32 s58, s47, s72
	s_setprio 1
	s_waitcnt lgkmcnt(3)
	v_mfma_f32_32x32x16_bf16 v[80:95], v[80:83], v[140:143], 0
	v_add_u32_e32 v0, v167, v159
	ds_read_b128 v[244:247], v0
	s_waitcnt lgkmcnt(3)
	v_mfma_f32_32x32x16_bf16 v[80:95], v[232:235], v[136:139], v[80:95]
	v_add_u32_e32 v0, v167, v160
	ds_read_b128 v[248:251], v0
	s_waitcnt lgkmcnt(3)
	v_mfma_f32_32x32x16_bf16 v[80:95], v[236:239], v[132:135], v[80:95]
	v_add_u32_e32 v0, v167, v161
	ds_read_b128 v[232:235], v0
	s_waitcnt lgkmcnt(3)
	v_mfma_f32_32x32x16_bf16 v[80:95], v[240:243], v[128:131], v[80:95]
	v_add_u32_e32 v0, v167, v162
	ds_read_b128 v[236:239], v0
	s_waitcnt lgkmcnt(3)
	v_mfma_f32_32x32x16_bf16 v[80:95], v[244:247], v[124:127], v[80:95]
	v_add_u32_e32 v0, v167, v163
	ds_read_b128 v[240:243], v0
	s_waitcnt lgkmcnt(3)
	v_mfma_f32_32x32x16_bf16 v[80:95], v[248:251], v[120:123], v[80:95]
	v_add_u32_e32 v0, v167, v164
	ds_read_b128 v[244:247], v0
	s_waitcnt lgkmcnt(3)
	v_mfma_f32_32x32x16_bf16 v[80:95], v[232:235], v[116:119], v[80:95]
	v_add_u32_e32 v0, v167, v165
	ds_read_b128 v[248:251], v0
	s_waitcnt lgkmcnt(3)
	v_mfma_f32_32x32x16_bf16 v[80:95], v[236:239], v[112:115], v[80:95]
	v_add_u32_e32 v0, v167, v166
	ds_read_b128 v[232:235], v0
	s_waitcnt lgkmcnt(3)
	v_mfma_f32_32x32x16_bf16 v[80:95], v[240:243], v[108:111], v[80:95]
	s_waitcnt lgkmcnt(2)
	v_mfma_f32_32x32x16_bf16 v[80:95], v[244:247], v[104:107], v[80:95]
	s_waitcnt lgkmcnt(1)
	v_mfma_f32_32x32x16_bf16 v[80:95], v[248:251], v[100:103], v[80:95]
	s_waitcnt lgkmcnt(0)
	v_mfma_f32_32x32x16_bf16 v[80:95], v[232:235], v[96:99], v[80:95]
	s_setprio 0
	s_cmpk_lg_i32 s58, 0x60
	s_cbranch_scc1 .LBB0_2426
	s_nop 8
	v_cndmask_b32_e64 v0, v80, v150, s[8:9]
	v_cndmask_b32_e64 v81, v150, v81, s[12:13]
	v_cndmask_b32_e64 v80, v0, v80, s[12:13]
	v_cndmask_b32_e64 v82, v82, v150, s[14:15]
	v_cndmask_b32_e64 v83, v83, v150, s[16:17]
	v_cndmask_b32_e64 v84, v84, v150, s[18:19]
	v_cndmask_b32_e64 v85, v85, v150, s[20:21]
	v_cndmask_b32_e64 v86, v86, v150, s[22:23]
	v_cndmask_b32_e64 v87, v87, v150, s[24:25]
	v_cndmask_b32_e64 v88, v88, v150, s[26:27]
	v_cndmask_b32_e64 v89, v89, v150, s[28:29]
	v_cndmask_b32_e64 v90, v90, v150, s[30:31]
	v_cndmask_b32_e64 v91, v91, v150, s[34:35]
	v_cndmask_b32_e64 v92, v92, v150, s[36:37]
	v_cndmask_b32_e64 v93, v93, v150, s[38:39]
	v_cndmask_b32_e64 v94, v94, v150, s[40:41]
	v_cndmask_b32_e64 v95, v95, v150, s[42:43]

.LBB0_2436:
	v_sub_f32_e32 v0, v80, v231
	v_exp_f32_e32 v9, v0
	v_sub_f32_e32 v0, v81, v231
	v_exp_f32_e32 v10, v0
	v_sub_f32_e32 v0, v82, v231
	v_exp_f32_e32 v4, v0
	v_sub_f32_e32 v0, v83, v231
	v_exp_f32_e32 v0, v0
	v_add_f32_e32 v5, v9, v10
	v_pk_add_f32 v[2:3], v[4:5], v[0:1]
	s_nop 0
	v_pk_add_f32 v[6:7], v[2:3], v[2:3] op_sel_hi:[0,1]
	v_sub_f32_e32 v2, v84, v231
	v_exp_f32_e32 v13, v2
	v_sub_f32_e32 v2, v85, v231
	v_exp_f32_e32 v14, v2
	v_sub_f32_e32 v2, v86, v231
	v_exp_f32_e32 v8, v2
	v_sub_f32_e32 v2, v87, v231
	v_exp_f32_e32 v6, v2
	v_cvt_pk_bf16_f32 v2, v9, v10
	v_add_f32_e32 v9, v13, v14
	v_cvt_pk_bf16_f32 v3, v4, v0
	v_pk_add_f32 v[4:5], v[8:9], v[6:7]
	v_sub_f32_e32 v0, v88, v231
	v_pk_add_f32 v[10:11], v[4:5], v[4:5] op_sel_hi:[0,1]
	v_sub_f32_e32 v4, v89, v231
	v_exp_f32_e32 v9, v4
	v_sub_f32_e32 v4, v90, v231
	v_exp_f32_e32 v0, v0
	v_exp_f32_e32 v12, v4
	v_sub_f32_e32 v4, v91, v231
	v_exp_f32_e32 v10, v4
	v_cvt_pk_bf16_f32 v4, v13, v14
	v_add_f32_e32 v13, v0, v9
	v_cvt_pk_bf16_f32 v5, v8, v6
	v_pk_add_f32 v[6:7], v[12:13], v[10:11]
	s_nop 0
	v_pk_add_f32 v[14:15], v[6:7], v[6:7] op_sel_hi:[0,1]
	v_sub_f32_e32 v6, v92, v231
	v_exp_f32_e32 v89, v6
	v_sub_f32_e32 v6, v93, v231
	v_exp_f32_e32 v90, v6
	v_sub_f32_e32 v6, v94, v231
	v_exp_f32_e32 v88, v6
	v_sub_f32_e32 v6, v95, v231
	v_exp_f32_e32 v14, v6
	v_cvt_pk_bf16_f32 v6, v0, v9
	v_cvt_pk_bf16_f32 v7, v12, v10
	v_cvt_pk_bf16_f32 v8, v89, v90
	v_cvt_pk_bf16_f32 v9, v88, v14
	ds_read_b64_tr_b16 v[10:11], v199
	ds_read_b64_tr_b16 v[12:13], v200
	ds_read_b64_tr_b16 v[80:81], v201
	ds_read_b64_tr_b16 v[82:83], v202
	ds_read_b64_tr_b16 v[84:85], v203
	ds_read_b64_tr_b16 v[86:87], v204
	v_add_f32_e32 v89, v89, v90
	v_pk_add_f32 v[14:15], v[88:89], v[14:15]
	s_nop 0
	v_add_f32_e32 v0, v14, v15
	v_add_f32_e32 v168, v168, v0
	s_setprio 1
	s_waitcnt lgkmcnt(4)
	v_mfma_f32_32x32x16_bf16 v[64:79], v[10:13], v[2:5], v[64:79]
	ds_read_b64_tr_b16 v[88:89], v226
	ds_read_b64_tr_b16 v[90:91], v205
	s_waitcnt lgkmcnt(4)
	v_mfma_f32_32x32x16_bf16 v[48:63], v[80:83], v[2:5], v[48:63]
	ds_read_b64_tr_b16 v[10:11], v206
	ds_read_b64_tr_b16 v[12:13], v227 offset:6144
	s_waitcnt lgkmcnt(4)
	v_mfma_f32_32x32x16_bf16 v[32:47], v[84:87], v[2:5], v[32:47]
	ds_read_b64_tr_b16 v[80:81], v207
	ds_read_b64_tr_b16 v[82:83], v228 offset:6144
	s_waitcnt lgkmcnt(4)
	v_mfma_f32_32x32x16_bf16 v[16:31], v[88:91], v[2:5], v[16:31]
	ds_read_b64_tr_b16 v[84:85], v208
	ds_read_b64_tr_b16 v[86:87], v229 offset:6144
	s_waitcnt lgkmcnt(4)
	v_mfma_f32_32x32x16_bf16 v[64:79], v[10:13], v[6:9], v[64:79]
	ds_read_b64_tr_b16 v[2:3], v209
	ds_read_b64_tr_b16 v[4:5], v230 offset:6144
	s_waitcnt lgkmcnt(4)
	v_mfma_f32_32x32x16_bf16 v[48:63], v[80:83], v[6:9], v[48:63]
	s_waitcnt lgkmcnt(2)
	v_mfma_f32_32x32x16_bf16 v[32:47], v[84:87], v[6:9], v[32:47]
	s_waitcnt lgkmcnt(0)
	v_mfma_f32_32x32x16_bf16 v[16:31], v[2:5], v[6:9], v[16:31]
	s_setprio 0
	s_cmp_gt_i32 s72, s71
	s_cbranch_scc1 .LBB0_2415
	v_add_u32_e32 v0, v167, v155
	v_add_u32_e32 v6, v167, v156
	ds_read_b128 v[2:5], v0 offset:24576
	ds_read_b128 v[6:9], v6 offset:24576
	v_add_u32_e32 v0, v167, v157
	v_add_u32_e32 v14, v167, v158
	ds_read_b128 v[10:13], v0 offset:24576
	ds_read_b128 v[232:235], v14 offset:24576
	s_setprio 1
	s_waitcnt lgkmcnt(3)
	v_mfma_f32_32x32x16_bf16 v[80:95], v[2:5], v[140:143], 0
	v_add_u32_e32 v0, v167, v159
	ds_read_b128 v[236:239], v0 offset:24576
	s_waitcnt lgkmcnt(3)
	v_mfma_f32_32x32x16_bf16 v[80:95], v[6:9], v[136:139], v[80:95]
	v_add_u32_e32 v0, v167, v160
	ds_read_b128 v[2:5], v0 offset:24576
	s_waitcnt lgkmcnt(3)
	v_mfma_f32_32x32x16_bf16 v[80:95], v[10:13], v[132:135], v[80:95]
	v_add_u32_e32 v0, v167, v161
	ds_read_b128 v[6:9], v0 offset:24576
	s_waitcnt lgkmcnt(3)
	v_mfma_f32_32x32x16_bf16 v[80:95], v[232:235], v[128:131], v[80:95]
	v_add_u32_e32 v0, v167, v162
	ds_read_b128 v[10:13], v0 offset:24576
	s_waitcnt lgkmcnt(3)
	v_mfma_f32_32x32x16_bf16 v[80:95], v[236:239], v[124:127], v[80:95]
	v_add_u32_e32 v0, v167, v163
	ds_read_b128 v[232:235], v0 offset:24576
	s_waitcnt lgkmcnt(3)
	v_mfma_f32_32x32x16_bf16 v[80:95], v[2:5], v[120:123], v[80:95]
	v_add_u32_e32 v0, v167, v164
	ds_read_b128 v[236:239], v0 offset:24576
	s_waitcnt lgkmcnt(3)
	v_mfma_f32_32x32x16_bf16 v[80:95], v[6:9], v[116:119], v[80:95]
	v_add_u32_e32 v0, v167, v165
	ds_read_b128 v[2:5], v0 offset:24576
	s_waitcnt lgkmcnt(3)
	v_mfma_f32_32x32x16_bf16 v[80:95], v[10:13], v[112:115], v[80:95]
	v_add_u32_e32 v0, v167, v166
	ds_read_b128 v[6:9], v0 offset:24576
	s_waitcnt lgkmcnt(3)
	v_mfma_f32_32x32x16_bf16 v[80:95], v[232:235], v[108:111], v[80:95]
	s_waitcnt lgkmcnt(2)
	v_mfma_f32_32x32x16_bf16 v[80:95], v[236:239], v[104:107], v[80:95]
	s_waitcnt lgkmcnt(1)
	v_mfma_f32_32x32x16_bf16 v[80:95], v[2:5], v[100:103], v[80:95]
	s_waitcnt lgkmcnt(0)
	v_mfma_f32_32x32x16_bf16 v[80:95], v[6:9], v[96:99], v[80:95]
	s_setprio 0
	s_cmp_lg_u32 s1, 0
	s_cbranch_scc1 .LBB0_2439
	s_nop 8
	v_cndmask_b32_e64 v0, v80, v150, s[8:9]
	v_cndmask_b32_e64 v81, v150, v81, s[12:13]
	v_cndmask_b32_e64 v80, v0, v80, s[12:13]
	v_cndmask_b32_e64 v82, v82, v150, s[14:15]
	v_cndmask_b32_e64 v83, v83, v150, s[16:17]
	v_cndmask_b32_e64 v84, v84, v150, s[18:19]
	v_cndmask_b32_e64 v85, v85, v150, s[20:21]
	v_cndmask_b32_e64 v86, v86, v150, s[22:23]
	v_cndmask_b32_e64 v87, v87, v150, s[24:25]
	v_cndmask_b32_e64 v88, v88, v150, s[26:27]
	v_cndmask_b32_e64 v89, v89, v150, s[28:29]
	v_cndmask_b32_e64 v90, v90, v150, s[30:31]
	v_cndmask_b32_e64 v91, v91, v150, s[34:35]
	v_cndmask_b32_e64 v92, v92, v150, s[36:37]
	v_cndmask_b32_e64 v93, v93, v150, s[38:39]
	v_cndmask_b32_e64 v94, v94, v150, s[40:41]
	v_cndmask_b32_e64 v95, v95, v150, s[42:43]

.LBB0_2472:
	v_sub_f32_e32 v0, v80, v234
	v_exp_f32_e32 v194, v0
	v_sub_f32_e32 v0, v81, v234
	v_exp_f32_e32 v195, v0
	v_sub_f32_e32 v0, v82, v234
	v_exp_f32_e32 v82, v0
	v_sub_f32_e32 v0, v83, v234
	v_exp_f32_e32 v0, v0
	v_add_f32_e32 v83, v194, v195
	v_pk_add_f32 v[80:81], v[82:83], v[0:1]
	s_nop 0
	v_pk_add_f32 v[192:193], v[80:81], v[80:81] op_sel_hi:[0,1]
	v_sub_f32_e32 v80, v84, v234
	v_exp_f32_e32 v236, v80
	v_sub_f32_e32 v80, v85, v234
	v_exp_f32_e32 v237, v80
	v_sub_f32_e32 v80, v86, v234
	v_exp_f32_e32 v84, v80
	v_sub_f32_e32 v80, v87, v234
	v_exp_f32_e32 v192, v80
	v_add_f32_e32 v85, v236, v237
	v_cvt_pk_bf16_f32 v80, v194, v195
	v_cvt_pk_bf16_f32 v81, v82, v0
	v_pk_add_f32 v[82:83], v[84:85], v[192:193]
	v_sub_f32_e32 v0, v88, v234
	v_pk_add_f32 v[86:87], v[82:83], v[82:83] op_sel_hi:[0,1]
	v_sub_f32_e32 v82, v89, v234
	v_exp_f32_e32 v193, v82
	v_sub_f32_e32 v82, v90, v234
	v_exp_f32_e32 v0, v0
	v_exp_f32_e32 v88, v82
	v_sub_f32_e32 v82, v91, v234
	v_exp_f32_e32 v86, v82
	v_add_f32_e32 v89, v0, v193
	v_cvt_pk_bf16_f32 v82, v236, v237
	v_cvt_pk_bf16_f32 v83, v84, v192
	v_pk_add_f32 v[84:85], v[88:89], v[86:87]
	s_nop 0
	v_pk_add_f32 v[236:237], v[84:85], v[84:85] op_sel_hi:[0,1]
	v_sub_f32_e32 v84, v92, v234
	v_exp_f32_e32 v239, v84
	v_sub_f32_e32 v84, v93, v234
	v_exp_f32_e32 v240, v84
	v_sub_f32_e32 v84, v94, v234
	v_exp_f32_e32 v238, v84
	v_sub_f32_e32 v84, v95, v234
	v_exp_f32_e32 v236, v84
	v_cvt_pk_bf16_f32 v84, v0, v193
	v_cvt_pk_bf16_f32 v85, v88, v86
	v_cvt_pk_bf16_f32 v86, v239, v240
	v_cvt_pk_bf16_f32 v87, v238, v236
	ds_read_b64_tr_b16 v[88:89], v180 offset:49152
	ds_read_b64_tr_b16 v[90:91], v181 offset:49152
	ds_read_b64_tr_b16 v[92:93], v182 offset:49152
	ds_read_b64_tr_b16 v[94:95], v183 offset:49152
	ds_read_b64_tr_b16 v[192:193], v184 offset:49152
	ds_read_b64_tr_b16 v[194:195], v185 offset:49152
	v_add_f32_e32 v239, v239, v240
	v_pk_add_f32 v[236:237], v[238:239], v[236:237]
	s_nop 0
	v_add_f32_e32 v0, v236, v237
	v_add_f32_e32 v179, v179, v0
	s_setprio 1
	s_waitcnt lgkmcnt(4)
	v_mfma_f32_32x32x16_bf16 v[64:79], v[88:91], v[80:83], v[64:79]
	ds_read_b64_tr_b16 v[236:237], v224 offset:49152
	ds_read_b64_tr_b16 v[238:239], v186 offset:49152
	s_waitcnt lgkmcnt(4)
	v_mfma_f32_32x32x16_bf16 v[48:63], v[92:95], v[80:83], v[48:63]
	ds_read_b64_tr_b16 v[88:89], v187 offset:49152
	ds_read_b64_tr_b16 v[90:91], v225 offset:55296
	s_waitcnt lgkmcnt(4)
	v_mfma_f32_32x32x16_bf16 v[32:47], v[192:195], v[80:83], v[32:47]
	ds_read_b64_tr_b16 v[92:93], v188 offset:49152
	ds_read_b64_tr_b16 v[94:95], v226 offset:55296
	s_waitcnt lgkmcnt(4)
	v_mfma_f32_32x32x16_bf16 v[16:31], v[236:239], v[80:83], v[16:31]
	ds_read_b64_tr_b16 v[192:193], v189 offset:49152
	ds_read_b64_tr_b16 v[194:195], v227 offset:55296
	s_waitcnt lgkmcnt(4)
	v_mfma_f32_32x32x16_bf16 v[64:79], v[88:91], v[84:87], v[64:79]
	ds_read_b64_tr_b16 v[80:81], v190 offset:49152
	ds_read_b64_tr_b16 v[82:83], v228 offset:55296
	s_waitcnt lgkmcnt(4)
	v_mfma_f32_32x32x16_bf16 v[48:63], v[92:95], v[84:87], v[48:63]
	s_waitcnt lgkmcnt(2)
	v_mfma_f32_32x32x16_bf16 v[32:47], v[192:195], v[84:87], v[32:47]
	s_waitcnt lgkmcnt(0)
	v_mfma_f32_32x32x16_bf16 v[16:31], v[80:83], v[84:87], v[16:31]
	s_setprio 0
	s_sub_i32 s4, s51, 64
	s_cmp_gt_i32 s4, s46
	s_cbranch_scc1 .LBB0_2478
	v_add_u32_e32 v0, v170, v152
	v_add_u32_e32 v84, v170, v153
	ds_read_b128 v[80:83], v0
	ds_read_b128 v[192:195], v84
	v_add_u32_e32 v0, v170, v154
	v_add_u32_e32 v84, v170, v155
	ds_read_b128 v[236:239], v0
	ds_read_b128 v[240:243], v84
	s_add_i32 s4, s47, s51
	s_setprio 1
	s_waitcnt lgkmcnt(3)
	v_mfma_f32_32x32x16_bf16 v[80:95], v[80:83], v[140:143], 0
	v_add_u32_e32 v0, v170, v156
	ds_read_b128 v[244:247], v0
	s_waitcnt lgkmcnt(3)
	v_mfma_f32_32x32x16_bf16 v[80:95], v[192:195], v[136:139], v[80:95]
	v_add_u32_e32 v0, v170, v157
	ds_read_b128 v[248:251], v0
	s_waitcnt lgkmcnt(3)
	v_mfma_f32_32x32x16_bf16 v[80:95], v[236:239], v[132:135], v[80:95]
	v_add_u32_e32 v0, v170, v164
	ds_read_b128 v[192:195], v0
	s_waitcnt lgkmcnt(3)
	v_mfma_f32_32x32x16_bf16 v[80:95], v[240:243], v[128:131], v[80:95]
	v_add_u32_e32 v0, v170, v165
	ds_read_b128 v[236:239], v0
	s_waitcnt lgkmcnt(3)
	v_mfma_f32_32x32x16_bf16 v[80:95], v[244:247], v[124:127], v[80:95]
	v_add_u32_e32 v0, v170, v166
	ds_read_b128 v[240:243], v0
	s_waitcnt lgkmcnt(3)
	v_mfma_f32_32x32x16_bf16 v[80:95], v[248:251], v[120:123], v[80:95]
	v_add_u32_e32 v0, v170, v167
	ds_read_b128 v[244:247], v0
	s_waitcnt lgkmcnt(3)
	v_mfma_f32_32x32x16_bf16 v[80:95], v[192:195], v[116:119], v[80:95]
	v_add_u32_e32 v0, v170, v168
	ds_read_b128 v[248:251], v0
	s_waitcnt lgkmcnt(3)
	v_mfma_f32_32x32x16_bf16 v[80:95], v[236:239], v[112:115], v[80:95]
	v_add_u32_e32 v0, v170, v169
	ds_read_b128 v[192:195], v0
	s_waitcnt lgkmcnt(3)
	v_mfma_f32_32x32x16_bf16 v[80:95], v[240:243], v[108:111], v[80:95]
	s_waitcnt lgkmcnt(2)
	v_mfma_f32_32x32x16_bf16 v[80:95], v[244:247], v[104:107], v[80:95]
	s_waitcnt lgkmcnt(1)
	v_mfma_f32_32x32x16_bf16 v[80:95], v[248:251], v[100:103], v[80:95]
	s_waitcnt lgkmcnt(0)
	v_mfma_f32_32x32x16_bf16 v[80:95], v[192:195], v[96:99], v[80:95]
	s_setprio 0
	s_cmpk_lg_i32 s4, 0x60
	s_cbranch_scc1 .LBB0_2475
	s_nop 8
	v_cndmask_b32_e64 v0, v80, v161, s[8:9]
	v_cndmask_b32_e64 v81, v161, v81, s[12:13]
	v_cndmask_b32_e64 v80, v0, v80, s[12:13]
	v_cndmask_b32_e64 v82, v82, v161, s[14:15]
	v_cndmask_b32_e64 v83, v83, v161, s[16:17]
	v_cndmask_b32_e64 v84, v84, v161, s[18:19]
	v_cndmask_b32_e64 v85, v85, v161, s[20:21]
	v_cndmask_b32_e64 v86, v86, v161, s[22:23]
	v_cndmask_b32_e64 v87, v87, v161, s[24:25]
	v_cndmask_b32_e64 v88, v88, v161, s[26:27]
	v_cndmask_b32_e64 v89, v89, v161, s[28:29]
	v_cndmask_b32_e64 v90, v90, v161, s[30:31]
	v_cndmask_b32_e64 v91, v91, v161, s[34:35]
	v_cndmask_b32_e64 v92, v92, v161, s[36:37]
	v_cndmask_b32_e64 v93, v93, v161, s[38:39]
	v_cndmask_b32_e64 v94, v94, v161, s[40:41]
	v_cndmask_b32_e64 v95, v95, v161, s[42:43]

.LBB0_2485:
	v_sub_f32_e32 v0, v80, v234
	v_exp_f32_e32 v9, v0
	v_sub_f32_e32 v0, v81, v234
	v_exp_f32_e32 v10, v0
	v_sub_f32_e32 v0, v82, v234
	v_exp_f32_e32 v4, v0
	v_sub_f32_e32 v0, v83, v234
	v_exp_f32_e32 v0, v0
	v_add_f32_e32 v5, v9, v10
	v_pk_add_f32 v[2:3], v[4:5], v[0:1]
	s_nop 0
	v_pk_add_f32 v[6:7], v[2:3], v[2:3] op_sel_hi:[0,1]
	v_sub_f32_e32 v2, v84, v234
	v_exp_f32_e32 v13, v2
	v_sub_f32_e32 v2, v85, v234
	v_exp_f32_e32 v14, v2
	v_sub_f32_e32 v2, v86, v234
	v_exp_f32_e32 v8, v2
	v_sub_f32_e32 v2, v87, v234
	v_exp_f32_e32 v6, v2
	v_cvt_pk_bf16_f32 v2, v9, v10
	v_add_f32_e32 v9, v13, v14
	v_cvt_pk_bf16_f32 v3, v4, v0
	v_pk_add_f32 v[4:5], v[8:9], v[6:7]
	v_sub_f32_e32 v0, v88, v234
	v_pk_add_f32 v[10:11], v[4:5], v[4:5] op_sel_hi:[0,1]
	v_sub_f32_e32 v4, v89, v234
	v_exp_f32_e32 v9, v4
	v_sub_f32_e32 v4, v90, v234
	v_exp_f32_e32 v0, v0
	v_exp_f32_e32 v12, v4
	v_sub_f32_e32 v4, v91, v234
	v_exp_f32_e32 v10, v4
	v_cvt_pk_bf16_f32 v4, v13, v14
	v_add_f32_e32 v13, v0, v9
	v_cvt_pk_bf16_f32 v5, v8, v6
	v_pk_add_f32 v[6:7], v[12:13], v[10:11]
	s_nop 0
	v_pk_add_f32 v[14:15], v[6:7], v[6:7] op_sel_hi:[0,1]
	v_sub_f32_e32 v6, v92, v234
	v_exp_f32_e32 v89, v6
	v_sub_f32_e32 v6, v93, v234
	v_exp_f32_e32 v90, v6
	v_sub_f32_e32 v6, v94, v234
	v_exp_f32_e32 v88, v6
	v_sub_f32_e32 v6, v95, v234
	v_exp_f32_e32 v14, v6
	v_cvt_pk_bf16_f32 v6, v0, v9
	v_cvt_pk_bf16_f32 v7, v12, v10
	v_cvt_pk_bf16_f32 v8, v89, v90
	v_cvt_pk_bf16_f32 v9, v88, v14
	ds_read_b64_tr_b16 v[10:11], v202
	ds_read_b64_tr_b16 v[12:13], v203
	ds_read_b64_tr_b16 v[80:81], v204
	ds_read_b64_tr_b16 v[82:83], v205
	ds_read_b64_tr_b16 v[84:85], v206
	ds_read_b64_tr_b16 v[86:87], v207
	v_add_f32_e32 v89, v89, v90
	v_pk_add_f32 v[14:15], v[88:89], v[14:15]
	s_nop 0
	v_add_f32_e32 v0, v14, v15
	v_add_f32_e32 v179, v179, v0
	s_setprio 1
	s_waitcnt lgkmcnt(4)
	v_mfma_f32_32x32x16_bf16 v[64:79], v[10:13], v[2:5], v[64:79]
	ds_read_b64_tr_b16 v[88:89], v229
	ds_read_b64_tr_b16 v[90:91], v208
	s_waitcnt lgkmcnt(4)
	v_mfma_f32_32x32x16_bf16 v[48:63], v[80:83], v[2:5], v[48:63]
	ds_read_b64_tr_b16 v[10:11], v209
	ds_read_b64_tr_b16 v[12:13], v230 offset:6144
	s_waitcnt lgkmcnt(4)
	v_mfma_f32_32x32x16_bf16 v[32:47], v[84:87], v[2:5], v[32:47]
	ds_read_b64_tr_b16 v[80:81], v210
	ds_read_b64_tr_b16 v[82:83], v231 offset:6144
	s_waitcnt lgkmcnt(4)
	v_mfma_f32_32x32x16_bf16 v[16:31], v[88:91], v[2:5], v[16:31]
	ds_read_b64_tr_b16 v[84:85], v211
	ds_read_b64_tr_b16 v[86:87], v232 offset:6144
	s_waitcnt lgkmcnt(4)
	v_mfma_f32_32x32x16_bf16 v[64:79], v[10:13], v[6:9], v[64:79]
	ds_read_b64_tr_b16 v[2:3], v212
	ds_read_b64_tr_b16 v[4:5], v233 offset:6144
	s_waitcnt lgkmcnt(4)
	v_mfma_f32_32x32x16_bf16 v[48:63], v[80:83], v[6:9], v[48:63]
	s_waitcnt lgkmcnt(2)
	v_mfma_f32_32x32x16_bf16 v[32:47], v[84:87], v[6:9], v[32:47]
	s_waitcnt lgkmcnt(0)
	v_mfma_f32_32x32x16_bf16 v[16:31], v[2:5], v[6:9], v[16:31]
	s_setprio 0
	s_cmp_gt_i32 s51, s46
	s_cbranch_scc1 .LBB0_2464
	v_add_u32_e32 v0, v170, v152
	v_add_u32_e32 v6, v170, v153
	ds_read_b128 v[2:5], v0 offset:24576
	ds_read_b128 v[6:9], v6 offset:24576
	v_add_u32_e32 v0, v170, v154
	v_add_u32_e32 v14, v170, v155
	ds_read_b128 v[10:13], v0 offset:24576
	ds_read_b128 v[192:195], v14 offset:24576
	s_setprio 1
	s_waitcnt lgkmcnt(3)
	v_mfma_f32_32x32x16_bf16 v[80:95], v[2:5], v[140:143], 0
	v_add_u32_e32 v0, v170, v156
	ds_read_b128 v[236:239], v0 offset:24576
	s_waitcnt lgkmcnt(3)
	v_mfma_f32_32x32x16_bf16 v[80:95], v[6:9], v[136:139], v[80:95]
	v_add_u32_e32 v0, v170, v157
	ds_read_b128 v[2:5], v0 offset:24576
	s_waitcnt lgkmcnt(3)
	v_mfma_f32_32x32x16_bf16 v[80:95], v[10:13], v[132:135], v[80:95]
	v_add_u32_e32 v0, v170, v164
	ds_read_b128 v[6:9], v0 offset:24576
	s_waitcnt lgkmcnt(3)
	v_mfma_f32_32x32x16_bf16 v[80:95], v[192:195], v[128:131], v[80:95]
	v_add_u32_e32 v0, v170, v165
	ds_read_b128 v[10:13], v0 offset:24576
	s_waitcnt lgkmcnt(3)
	v_mfma_f32_32x32x16_bf16 v[80:95], v[236:239], v[124:127], v[80:95]
	v_add_u32_e32 v0, v170, v166
	ds_read_b128 v[192:195], v0 offset:24576
	s_waitcnt lgkmcnt(3)
	v_mfma_f32_32x32x16_bf16 v[80:95], v[2:5], v[120:123], v[80:95]
	v_add_u32_e32 v0, v170, v167
	ds_read_b128 v[236:239], v0 offset:24576
	s_waitcnt lgkmcnt(3)
	v_mfma_f32_32x32x16_bf16 v[80:95], v[6:9], v[116:119], v[80:95]
	v_add_u32_e32 v0, v170, v168
	ds_read_b128 v[2:5], v0 offset:24576
	s_waitcnt lgkmcnt(3)
	v_mfma_f32_32x32x16_bf16 v[80:95], v[10:13], v[112:115], v[80:95]
	v_add_u32_e32 v0, v170, v169
	ds_read_b128 v[6:9], v0 offset:24576
	s_waitcnt lgkmcnt(3)
	v_mfma_f32_32x32x16_bf16 v[80:95], v[192:195], v[108:111], v[80:95]
	s_waitcnt lgkmcnt(2)
	v_mfma_f32_32x32x16_bf16 v[80:95], v[236:239], v[104:107], v[80:95]
	s_waitcnt lgkmcnt(1)
	v_mfma_f32_32x32x16_bf16 v[80:95], v[2:5], v[100:103], v[80:95]
	s_waitcnt lgkmcnt(0)
	v_mfma_f32_32x32x16_bf16 v[80:95], v[6:9], v[96:99], v[80:95]
	s_setprio 0
	s_cmp_lg_u32 s77, 0
	s_cbranch_scc1 .LBB0_2488
	s_nop 8
	v_cndmask_b32_e64 v0, v80, v161, s[8:9]
	v_cndmask_b32_e64 v81, v161, v81, s[12:13]
	v_cndmask_b32_e64 v80, v0, v80, s[12:13]
	v_cndmask_b32_e64 v82, v82, v161, s[14:15]
	v_cndmask_b32_e64 v83, v83, v161, s[16:17]
	v_cndmask_b32_e64 v84, v84, v161, s[18:19]
	v_cndmask_b32_e64 v85, v85, v161, s[20:21]
	v_cndmask_b32_e64 v86, v86, v161, s[22:23]
	v_cndmask_b32_e64 v87, v87, v161, s[24:25]
	v_cndmask_b32_e64 v88, v88, v161, s[26:27]
	v_cndmask_b32_e64 v89, v89, v161, s[28:29]
	v_cndmask_b32_e64 v90, v90, v161, s[30:31]
	v_cndmask_b32_e64 v91, v91, v161, s[34:35]
	v_cndmask_b32_e64 v92, v92, v161, s[36:37]
	v_cndmask_b32_e64 v93, v93, v161, s[38:39]
	v_cndmask_b32_e64 v94, v94, v161, s[40:41]
	v_cndmask_b32_e64 v95, v95, v161, s[42:43]

.LBB0_3682:
	v_sub_f32_e32 v0, v80, v232
	v_exp_f32_e32 v233, v0
	v_sub_f32_e32 v0, v81, v232
	v_exp_f32_e32 v236, v0
	v_sub_f32_e32 v0, v82, v232
	v_exp_f32_e32 v82, v0
	v_sub_f32_e32 v0, v83, v232
	v_exp_f32_e32 v0, v0
	v_add_f32_e32 v83, v233, v236
	v_pk_add_f32 v[80:81], v[82:83], v[0:1]
	s_nop 0
	v_pk_add_f32 v[234:235], v[80:81], v[80:81] op_sel_hi:[0,1]
	v_sub_f32_e32 v80, v84, v232
	v_exp_f32_e32 v237, v80
	v_sub_f32_e32 v80, v85, v232
	v_exp_f32_e32 v238, v80
	v_sub_f32_e32 v80, v86, v232
	v_exp_f32_e32 v84, v80
	v_sub_f32_e32 v80, v87, v232
	v_exp_f32_e32 v234, v80
	v_add_f32_e32 v85, v237, v238
	v_cvt_pk_bf16_f32 v80, v233, v236
	v_cvt_pk_bf16_f32 v81, v82, v0
	v_pk_add_f32 v[82:83], v[84:85], v[234:235]
	v_sub_f32_e32 v0, v88, v232
	v_pk_add_f32 v[86:87], v[82:83], v[82:83] op_sel_hi:[0,1]
	v_sub_f32_e32 v82, v89, v232
	v_exp_f32_e32 v233, v82
	v_sub_f32_e32 v82, v90, v232
	v_exp_f32_e32 v0, v0
	v_exp_f32_e32 v88, v82
	v_sub_f32_e32 v82, v91, v232
	v_exp_f32_e32 v86, v82
	v_add_f32_e32 v89, v0, v233
	v_cvt_pk_bf16_f32 v82, v237, v238
	v_cvt_pk_bf16_f32 v83, v84, v234
	v_pk_add_f32 v[84:85], v[88:89], v[86:87]
	s_nop 0
	v_pk_add_f32 v[238:239], v[84:85], v[84:85] op_sel_hi:[0,1]
	v_sub_f32_e32 v84, v92, v232
	v_exp_f32_e32 v241, v84
	v_sub_f32_e32 v84, v93, v232
	v_exp_f32_e32 v242, v84
	v_sub_f32_e32 v84, v94, v232
	v_exp_f32_e32 v240, v84
	v_sub_f32_e32 v84, v95, v232
	v_exp_f32_e32 v238, v84
	v_cvt_pk_bf16_f32 v84, v0, v233
	v_cvt_pk_bf16_f32 v85, v88, v86
	v_cvt_pk_bf16_f32 v86, v241, v242
	v_cvt_pk_bf16_f32 v87, v240, v238
	ds_read_b64_tr_b16 v[88:89], v178 offset:49152
	ds_read_b64_tr_b16 v[90:91], v179 offset:49152
	ds_read_b64_tr_b16 v[92:93], v180 offset:49152
	ds_read_b64_tr_b16 v[94:95], v181 offset:49152
	ds_read_b64_tr_b16 v[234:235], v182 offset:49152
	ds_read_b64_tr_b16 v[236:237], v183 offset:49152
	v_add_f32_e32 v241, v241, v242
	v_pk_add_f32 v[238:239], v[240:241], v[238:239]
	s_nop 0
	v_add_f32_e32 v0, v238, v239
	v_add_f32_e32 v169, v169, v0
	s_setprio 1
	s_waitcnt lgkmcnt(4)
	v_mfma_f32_32x32x16_bf16 v[64:79], v[88:91], v[80:83], v[64:79]
	ds_read_b64_tr_b16 v[238:239], v222 offset:49152
	ds_read_b64_tr_b16 v[240:241], v184 offset:49152
	s_waitcnt lgkmcnt(4)
	v_mfma_f32_32x32x16_bf16 v[48:63], v[92:95], v[80:83], v[48:63]
	ds_read_b64_tr_b16 v[88:89], v185 offset:49152
	ds_read_b64_tr_b16 v[90:91], v223 offset:55296
	s_waitcnt lgkmcnt(4)
	v_mfma_f32_32x32x16_bf16 v[32:47], v[234:237], v[80:83], v[32:47]
	ds_read_b64_tr_b16 v[92:93], v186 offset:49152
	ds_read_b64_tr_b16 v[94:95], v224 offset:55296
	s_waitcnt lgkmcnt(4)
	v_mfma_f32_32x32x16_bf16 v[16:31], v[238:241], v[80:83], v[16:31]
	ds_read_b64_tr_b16 v[234:235], v187 offset:49152
	ds_read_b64_tr_b16 v[236:237], v225 offset:55296
	s_waitcnt lgkmcnt(4)
	v_mfma_f32_32x32x16_bf16 v[64:79], v[88:91], v[84:87], v[64:79]
	ds_read_b64_tr_b16 v[80:81], v188 offset:49152
	ds_read_b64_tr_b16 v[82:83], v226 offset:55296
	s_waitcnt lgkmcnt(4)
	v_mfma_f32_32x32x16_bf16 v[48:63], v[92:95], v[84:87], v[48:63]
	s_waitcnt lgkmcnt(2)
	v_mfma_f32_32x32x16_bf16 v[32:47], v[234:237], v[84:87], v[32:47]
	s_waitcnt lgkmcnt(0)
	v_mfma_f32_32x32x16_bf16 v[16:31], v[80:83], v[84:87], v[16:31]
	s_setprio 0
	s_sub_i32 s62, s68, 64
	s_cmp_gt_i32 s62, s46
	s_cbranch_scc1 .LBB0_3688
	v_add_u32_e32 v0, v168, v156
	v_add_u32_e32 v84, v168, v157
	ds_read_b128 v[80:83], v0
	ds_read_b128 v[234:237], v84
	v_add_u32_e32 v0, v168, v158
	v_add_u32_e32 v84, v168, v159
	ds_read_b128 v[238:241], v0
	ds_read_b128 v[242:245], v84
	s_add_i32 s62, s67, s68
	s_setprio 1
	s_waitcnt lgkmcnt(3)
	v_mfma_f32_32x32x16_bf16 v[80:95], v[80:83], v[140:143], 0
	v_add_u32_e32 v0, v168, v160
	ds_read_b128 v[246:249], v0
	s_waitcnt lgkmcnt(3)
	v_mfma_f32_32x32x16_bf16 v[80:95], v[234:237], v[136:139], v[80:95]
	v_add_u32_e32 v0, v168, v161
	ds_read_b128 v[250:253], v0
	s_waitcnt lgkmcnt(3)
	v_mfma_f32_32x32x16_bf16 v[80:95], v[238:241], v[132:135], v[80:95]
	v_add_u32_e32 v0, v168, v162
	ds_read_b128 v[234:237], v0
	s_waitcnt lgkmcnt(3)
	v_mfma_f32_32x32x16_bf16 v[80:95], v[242:245], v[128:131], v[80:95]
	v_add_u32_e32 v0, v168, v163
	ds_read_b128 v[238:241], v0
	s_waitcnt lgkmcnt(3)
	v_mfma_f32_32x32x16_bf16 v[80:95], v[246:249], v[124:127], v[80:95]
	v_add_u32_e32 v0, v168, v164
	ds_read_b128 v[242:245], v0
	s_waitcnt lgkmcnt(3)
	v_mfma_f32_32x32x16_bf16 v[80:95], v[250:253], v[120:123], v[80:95]
	v_add_u32_e32 v0, v168, v165
	ds_read_b128 v[246:249], v0
	s_waitcnt lgkmcnt(3)
	v_mfma_f32_32x32x16_bf16 v[80:95], v[234:237], v[116:119], v[80:95]
	v_add_u32_e32 v0, v168, v166
	ds_read_b128 v[250:253], v0
	s_waitcnt lgkmcnt(3)
	v_mfma_f32_32x32x16_bf16 v[80:95], v[238:241], v[112:115], v[80:95]
	v_add_u32_e32 v0, v168, v167
	ds_read_b128 v[234:237], v0
	s_waitcnt lgkmcnt(3)
	v_mfma_f32_32x32x16_bf16 v[80:95], v[242:245], v[108:111], v[80:95]
	s_waitcnt lgkmcnt(2)
	v_mfma_f32_32x32x16_bf16 v[80:95], v[246:249], v[104:107], v[80:95]
	s_waitcnt lgkmcnt(1)
	v_mfma_f32_32x32x16_bf16 v[80:95], v[250:253], v[100:103], v[80:95]
	s_waitcnt lgkmcnt(0)
	v_mfma_f32_32x32x16_bf16 v[80:95], v[234:237], v[96:99], v[80:95]
	s_setprio 0
	s_cmpk_lg_i32 s62, 0x60
	s_cbranch_scc1 .LBB0_3685
	s_nop 8
	v_cndmask_b32_e64 v0, v80, v150, s[8:9]
	v_cndmask_b32_e64 v81, v150, v81, s[10:11]
	v_cndmask_b32_e64 v80, v0, v80, s[10:11]
	v_cndmask_b32_e64 v82, v82, v150, s[12:13]
	v_cndmask_b32_e64 v83, v83, v150, s[14:15]
	v_cndmask_b32_e64 v84, v84, v150, s[16:17]
	v_cndmask_b32_e64 v85, v85, v150, s[18:19]
	v_cndmask_b32_e64 v86, v86, v150, s[20:21]
	v_cndmask_b32_e64 v87, v87, v150, s[22:23]
	v_cndmask_b32_e64 v88, v88, v150, s[24:25]
	v_cndmask_b32_e64 v89, v89, v150, s[26:27]
	v_cndmask_b32_e64 v90, v90, v150, s[28:29]
	v_cndmask_b32_e64 v91, v91, v150, s[30:31]
	v_cndmask_b32_e64 v92, v92, v150, s[34:35]
	v_cndmask_b32_e64 v93, v93, v150, s[36:37]
	v_cndmask_b32_e64 v94, v94, v150, s[38:39]
	v_cndmask_b32_e64 v95, v95, v150, s[40:41]

.LBB0_3695:
	v_sub_f32_e32 v0, v80, v232
	v_exp_f32_e32 v9, v0
	v_sub_f32_e32 v0, v81, v232
	v_exp_f32_e32 v10, v0
	v_sub_f32_e32 v0, v82, v232
	v_exp_f32_e32 v4, v0
	v_sub_f32_e32 v0, v83, v232
	v_exp_f32_e32 v0, v0
	v_add_f32_e32 v5, v9, v10
	v_pk_add_f32 v[2:3], v[4:5], v[0:1]
	s_nop 0
	v_pk_add_f32 v[6:7], v[2:3], v[2:3] op_sel_hi:[0,1]
	v_sub_f32_e32 v2, v84, v232
	v_exp_f32_e32 v13, v2
	v_sub_f32_e32 v2, v85, v232
	v_exp_f32_e32 v14, v2
	v_sub_f32_e32 v2, v86, v232
	v_exp_f32_e32 v8, v2
	v_sub_f32_e32 v2, v87, v232
	v_exp_f32_e32 v6, v2
	v_cvt_pk_bf16_f32 v2, v9, v10
	v_add_f32_e32 v9, v13, v14
	v_cvt_pk_bf16_f32 v3, v4, v0
	v_pk_add_f32 v[4:5], v[8:9], v[6:7]
	v_sub_f32_e32 v0, v88, v232
	v_pk_add_f32 v[10:11], v[4:5], v[4:5] op_sel_hi:[0,1]
	v_sub_f32_e32 v4, v89, v232
	v_exp_f32_e32 v9, v4
	v_sub_f32_e32 v4, v90, v232
	v_exp_f32_e32 v0, v0
	v_exp_f32_e32 v12, v4
	v_sub_f32_e32 v4, v91, v232
	v_exp_f32_e32 v10, v4
	v_cvt_pk_bf16_f32 v4, v13, v14
	v_add_f32_e32 v13, v0, v9
	v_cvt_pk_bf16_f32 v5, v8, v6
	v_pk_add_f32 v[6:7], v[12:13], v[10:11]
	s_nop 0
	v_pk_add_f32 v[14:15], v[6:7], v[6:7] op_sel_hi:[0,1]
	v_sub_f32_e32 v6, v92, v232
	v_exp_f32_e32 v89, v6
	v_sub_f32_e32 v6, v93, v232
	v_exp_f32_e32 v90, v6
	v_sub_f32_e32 v6, v94, v232
	v_exp_f32_e32 v88, v6
	v_sub_f32_e32 v6, v95, v232
	v_exp_f32_e32 v14, v6
	v_cvt_pk_bf16_f32 v6, v0, v9
	v_cvt_pk_bf16_f32 v7, v12, v10
	v_cvt_pk_bf16_f32 v8, v89, v90
	v_cvt_pk_bf16_f32 v9, v88, v14
	ds_read_b64_tr_b16 v[10:11], v200
	ds_read_b64_tr_b16 v[12:13], v201
	ds_read_b64_tr_b16 v[80:81], v202
	ds_read_b64_tr_b16 v[82:83], v203
	ds_read_b64_tr_b16 v[84:85], v204
	ds_read_b64_tr_b16 v[86:87], v205
	v_add_f32_e32 v89, v89, v90
	v_pk_add_f32 v[14:15], v[88:89], v[14:15]
	s_nop 0
	v_add_f32_e32 v0, v14, v15
	v_add_f32_e32 v169, v169, v0
	s_setprio 1
	s_waitcnt lgkmcnt(4)
	v_mfma_f32_32x32x16_bf16 v[64:79], v[10:13], v[2:5], v[64:79]
	ds_read_b64_tr_b16 v[88:89], v227
	ds_read_b64_tr_b16 v[90:91], v206
	s_waitcnt lgkmcnt(4)
	v_mfma_f32_32x32x16_bf16 v[48:63], v[80:83], v[2:5], v[48:63]
	ds_read_b64_tr_b16 v[10:11], v207
	ds_read_b64_tr_b16 v[12:13], v228 offset:6144
	s_waitcnt lgkmcnt(4)
	v_mfma_f32_32x32x16_bf16 v[32:47], v[84:87], v[2:5], v[32:47]
	ds_read_b64_tr_b16 v[80:81], v208
	ds_read_b64_tr_b16 v[82:83], v229 offset:6144
	s_waitcnt lgkmcnt(4)
	v_mfma_f32_32x32x16_bf16 v[16:31], v[88:91], v[2:5], v[16:31]
	ds_read_b64_tr_b16 v[84:85], v209
	ds_read_b64_tr_b16 v[86:87], v230 offset:6144
	s_waitcnt lgkmcnt(4)
	v_mfma_f32_32x32x16_bf16 v[64:79], v[10:13], v[6:9], v[64:79]
	ds_read_b64_tr_b16 v[2:3], v210
	ds_read_b64_tr_b16 v[4:5], v231 offset:6144
	s_waitcnt lgkmcnt(4)
	v_mfma_f32_32x32x16_bf16 v[48:63], v[80:83], v[6:9], v[48:63]
	s_waitcnt lgkmcnt(2)
	v_mfma_f32_32x32x16_bf16 v[32:47], v[84:87], v[6:9], v[32:47]
	s_waitcnt lgkmcnt(0)
	v_mfma_f32_32x32x16_bf16 v[16:31], v[2:5], v[6:9], v[16:31]
	s_setprio 0
	s_cmp_gt_i32 s68, s46
	s_cbranch_scc1 .LBB0_3674
	v_add_u32_e32 v0, v168, v156
	v_add_u32_e32 v6, v168, v157
	ds_read_b128 v[2:5], v0 offset:24576
	ds_read_b128 v[6:9], v6 offset:24576
	v_add_u32_e32 v0, v168, v158
	v_add_u32_e32 v14, v168, v159
	ds_read_b128 v[10:13], v0 offset:24576
	ds_read_b128 v[234:237], v14 offset:24576
	s_setprio 1
	s_waitcnt lgkmcnt(3)
	v_mfma_f32_32x32x16_bf16 v[80:95], v[2:5], v[140:143], 0
	v_add_u32_e32 v0, v168, v160
	ds_read_b128 v[238:241], v0 offset:24576
	s_waitcnt lgkmcnt(3)
	v_mfma_f32_32x32x16_bf16 v[80:95], v[6:9], v[136:139], v[80:95]
	v_add_u32_e32 v0, v168, v161
	ds_read_b128 v[2:5], v0 offset:24576
	s_waitcnt lgkmcnt(3)
	v_mfma_f32_32x32x16_bf16 v[80:95], v[10:13], v[132:135], v[80:95]
	v_add_u32_e32 v0, v168, v162
	ds_read_b128 v[6:9], v0 offset:24576
	s_waitcnt lgkmcnt(3)
	v_mfma_f32_32x32x16_bf16 v[80:95], v[234:237], v[128:131], v[80:95]
	v_add_u32_e32 v0, v168, v163
	ds_read_b128 v[10:13], v0 offset:24576
	s_waitcnt lgkmcnt(3)
	v_mfma_f32_32x32x16_bf16 v[80:95], v[238:241], v[124:127], v[80:95]
	v_add_u32_e32 v0, v168, v164
	ds_read_b128 v[234:237], v0 offset:24576
	s_waitcnt lgkmcnt(3)
	v_mfma_f32_32x32x16_bf16 v[80:95], v[2:5], v[120:123], v[80:95]
	v_add_u32_e32 v0, v168, v165
	ds_read_b128 v[238:241], v0 offset:24576
	s_waitcnt lgkmcnt(3)
	v_mfma_f32_32x32x16_bf16 v[80:95], v[6:9], v[116:119], v[80:95]
	v_add_u32_e32 v0, v168, v166
	ds_read_b128 v[2:5], v0 offset:24576
	s_waitcnt lgkmcnt(3)
	v_mfma_f32_32x32x16_bf16 v[80:95], v[10:13], v[112:115], v[80:95]
	v_add_u32_e32 v0, v168, v167
	ds_read_b128 v[6:9], v0 offset:24576
	s_waitcnt lgkmcnt(3)
	v_mfma_f32_32x32x16_bf16 v[80:95], v[234:237], v[108:111], v[80:95]
	s_waitcnt lgkmcnt(2)
	v_mfma_f32_32x32x16_bf16 v[80:95], v[238:241], v[104:107], v[80:95]
	s_waitcnt lgkmcnt(1)
	v_mfma_f32_32x32x16_bf16 v[80:95], v[2:5], v[100:103], v[80:95]
	s_waitcnt lgkmcnt(0)
	v_mfma_f32_32x32x16_bf16 v[80:95], v[6:9], v[96:99], v[80:95]
	s_setprio 0
	s_cmp_lg_u32 s1, 0
	s_cbranch_scc1 .LBB0_3698
	s_nop 8
	v_cndmask_b32_e64 v0, v80, v150, s[8:9]
	v_cndmask_b32_e64 v81, v150, v81, s[10:11]
	v_cndmask_b32_e64 v80, v0, v80, s[10:11]
	v_cndmask_b32_e64 v82, v82, v150, s[12:13]
	v_cndmask_b32_e64 v83, v83, v150, s[14:15]
	v_cndmask_b32_e64 v84, v84, v150, s[16:17]
	v_cndmask_b32_e64 v85, v85, v150, s[18:19]
	v_cndmask_b32_e64 v86, v86, v150, s[20:21]
	v_cndmask_b32_e64 v87, v87, v150, s[22:23]
	v_cndmask_b32_e64 v88, v88, v150, s[24:25]
	v_cndmask_b32_e64 v89, v89, v150, s[26:27]
	v_cndmask_b32_e64 v90, v90, v150, s[28:29]
	v_cndmask_b32_e64 v91, v91, v150, s[30:31]
	v_cndmask_b32_e64 v92, v92, v150, s[34:35]
	v_cndmask_b32_e64 v93, v93, v150, s[36:37]
	v_cndmask_b32_e64 v94, v94, v150, s[38:39]
	v_cndmask_b32_e64 v95, v95, v150, s[40:41]

.LBB0_3734:
	v_sub_f32_e32 v0, v80, v231
	v_exp_f32_e32 v234, v0
	v_sub_f32_e32 v0, v81, v231
	v_exp_f32_e32 v235, v0
	v_sub_f32_e32 v0, v82, v231
	v_exp_f32_e32 v82, v0
	v_sub_f32_e32 v0, v83, v231
	v_exp_f32_e32 v0, v0
	v_add_f32_e32 v83, v234, v235
	v_pk_add_f32 v[80:81], v[82:83], v[0:1]
	s_nop 0
	v_pk_add_f32 v[232:233], v[80:81], v[80:81] op_sel_hi:[0,1]
	v_sub_f32_e32 v80, v84, v231
	v_exp_f32_e32 v236, v80
	v_sub_f32_e32 v80, v85, v231
	v_exp_f32_e32 v237, v80
	v_sub_f32_e32 v80, v86, v231
	v_exp_f32_e32 v84, v80
	v_sub_f32_e32 v80, v87, v231
	v_exp_f32_e32 v232, v80
	v_add_f32_e32 v85, v236, v237
	v_cvt_pk_bf16_f32 v80, v234, v235
	v_cvt_pk_bf16_f32 v81, v82, v0
	v_pk_add_f32 v[82:83], v[84:85], v[232:233]
	v_sub_f32_e32 v0, v88, v231
	v_pk_add_f32 v[86:87], v[82:83], v[82:83] op_sel_hi:[0,1]
	v_sub_f32_e32 v82, v89, v231
	v_exp_f32_e32 v233, v82
	v_sub_f32_e32 v82, v90, v231
	v_exp_f32_e32 v0, v0
	v_exp_f32_e32 v88, v82
	v_sub_f32_e32 v82, v91, v231
	v_exp_f32_e32 v86, v82
	v_add_f32_e32 v89, v0, v233
	v_cvt_pk_bf16_f32 v82, v236, v237
	v_cvt_pk_bf16_f32 v83, v84, v232
	v_pk_add_f32 v[84:85], v[88:89], v[86:87]
	s_nop 0
	v_pk_add_f32 v[236:237], v[84:85], v[84:85] op_sel_hi:[0,1]
	v_sub_f32_e32 v84, v92, v231
	v_exp_f32_e32 v239, v84
	v_sub_f32_e32 v84, v93, v231
	v_exp_f32_e32 v240, v84
	v_sub_f32_e32 v84, v94, v231
	v_exp_f32_e32 v238, v84
	v_sub_f32_e32 v84, v95, v231
	v_exp_f32_e32 v236, v84
	v_cvt_pk_bf16_f32 v84, v0, v233
	v_cvt_pk_bf16_f32 v85, v88, v86
	v_cvt_pk_bf16_f32 v86, v239, v240
	v_cvt_pk_bf16_f32 v87, v238, v236
	ds_read_b64_tr_b16 v[88:89], v177 offset:49152
	ds_read_b64_tr_b16 v[90:91], v178 offset:49152
	ds_read_b64_tr_b16 v[92:93], v179 offset:49152
	ds_read_b64_tr_b16 v[94:95], v180 offset:49152
	ds_read_b64_tr_b16 v[232:233], v181 offset:49152
	ds_read_b64_tr_b16 v[234:235], v182 offset:49152
	v_add_f32_e32 v239, v239, v240
	v_pk_add_f32 v[236:237], v[238:239], v[236:237]
	s_nop 0
	v_add_f32_e32 v0, v236, v237
	v_add_f32_e32 v168, v168, v0
	s_setprio 1
	s_waitcnt lgkmcnt(4)
	v_mfma_f32_32x32x16_bf16 v[64:79], v[88:91], v[80:83], v[64:79]
	ds_read_b64_tr_b16 v[236:237], v221 offset:49152
	ds_read_b64_tr_b16 v[238:239], v183 offset:49152
	s_waitcnt lgkmcnt(4)
	v_mfma_f32_32x32x16_bf16 v[48:63], v[92:95], v[80:83], v[48:63]
	ds_read_b64_tr_b16 v[88:89], v184 offset:49152
	ds_read_b64_tr_b16 v[90:91], v222 offset:55296
	s_waitcnt lgkmcnt(4)
	v_mfma_f32_32x32x16_bf16 v[32:47], v[232:235], v[80:83], v[32:47]
	ds_read_b64_tr_b16 v[92:93], v185 offset:49152
	ds_read_b64_tr_b16 v[94:95], v223 offset:55296
	s_waitcnt lgkmcnt(4)
	v_mfma_f32_32x32x16_bf16 v[16:31], v[236:239], v[80:83], v[16:31]
	ds_read_b64_tr_b16 v[232:233], v186 offset:49152
	ds_read_b64_tr_b16 v[234:235], v224 offset:55296
	s_waitcnt lgkmcnt(4)
	v_mfma_f32_32x32x16_bf16 v[64:79], v[88:91], v[84:87], v[64:79]
	ds_read_b64_tr_b16 v[80:81], v187 offset:49152
	ds_read_b64_tr_b16 v[82:83], v225 offset:55296
	s_waitcnt lgkmcnt(4)
	v_mfma_f32_32x32x16_bf16 v[48:63], v[92:95], v[84:87], v[48:63]
	s_waitcnt lgkmcnt(2)
	v_mfma_f32_32x32x16_bf16 v[32:47], v[232:235], v[84:87], v[32:47]
	s_waitcnt lgkmcnt(0)
	v_mfma_f32_32x32x16_bf16 v[16:31], v[80:83], v[84:87], v[16:31]
	s_setprio 0
	s_sub_i32 s50, s74, 64
	s_cmp_gt_i32 s50, s46
	s_cbranch_scc1 .LBB0_3740
	v_add_u32_e32 v0, v167, v155
	v_add_u32_e32 v84, v167, v156
	ds_read_b128 v[80:83], v0
	ds_read_b128 v[232:235], v84
	v_add_u32_e32 v0, v167, v157
	v_add_u32_e32 v84, v167, v158
	ds_read_b128 v[236:239], v0
	ds_read_b128 v[240:243], v84
	s_add_i32 s50, s2, s74
	s_setprio 1
	s_waitcnt lgkmcnt(3)
	v_mfma_f32_32x32x16_bf16 v[80:95], v[80:83], v[140:143], 0
	v_add_u32_e32 v0, v167, v159
	ds_read_b128 v[244:247], v0
	s_waitcnt lgkmcnt(3)
	v_mfma_f32_32x32x16_bf16 v[80:95], v[232:235], v[136:139], v[80:95]
	v_add_u32_e32 v0, v167, v160
	ds_read_b128 v[248:251], v0
	s_waitcnt lgkmcnt(3)
	v_mfma_f32_32x32x16_bf16 v[80:95], v[236:239], v[132:135], v[80:95]
	v_add_u32_e32 v0, v167, v161
	ds_read_b128 v[232:235], v0
	s_waitcnt lgkmcnt(3)
	v_mfma_f32_32x32x16_bf16 v[80:95], v[240:243], v[128:131], v[80:95]
	v_add_u32_e32 v0, v167, v162
	ds_read_b128 v[236:239], v0
	s_waitcnt lgkmcnt(3)
	v_mfma_f32_32x32x16_bf16 v[80:95], v[244:247], v[124:127], v[80:95]
	v_add_u32_e32 v0, v167, v163
	ds_read_b128 v[240:243], v0
	s_waitcnt lgkmcnt(3)
	v_mfma_f32_32x32x16_bf16 v[80:95], v[248:251], v[120:123], v[80:95]
	v_add_u32_e32 v0, v167, v164
	ds_read_b128 v[244:247], v0
	s_waitcnt lgkmcnt(3)
	v_mfma_f32_32x32x16_bf16 v[80:95], v[232:235], v[116:119], v[80:95]
	v_add_u32_e32 v0, v167, v165
	ds_read_b128 v[248:251], v0
	s_waitcnt lgkmcnt(3)
	v_mfma_f32_32x32x16_bf16 v[80:95], v[236:239], v[112:115], v[80:95]
	v_add_u32_e32 v0, v167, v166
	ds_read_b128 v[232:235], v0
	s_waitcnt lgkmcnt(3)
	v_mfma_f32_32x32x16_bf16 v[80:95], v[240:243], v[108:111], v[80:95]
	s_waitcnt lgkmcnt(2)
	v_mfma_f32_32x32x16_bf16 v[80:95], v[244:247], v[104:107], v[80:95]
	s_waitcnt lgkmcnt(1)
	v_mfma_f32_32x32x16_bf16 v[80:95], v[248:251], v[100:103], v[80:95]
	s_waitcnt lgkmcnt(0)
	v_mfma_f32_32x32x16_bf16 v[80:95], v[232:235], v[96:99], v[80:95]
	s_setprio 0
	s_cmpk_lg_i32 s50, 0x60
	s_cbranch_scc1 .LBB0_3737
	s_nop 8
	v_cndmask_b32_e64 v0, v80, v150, s[8:9]
	v_cndmask_b32_e64 v81, v150, v81, s[10:11]
	v_cndmask_b32_e64 v80, v0, v80, s[10:11]
	v_cndmask_b32_e64 v82, v82, v150, s[12:13]
	v_cndmask_b32_e64 v83, v83, v150, s[14:15]
	v_cndmask_b32_e64 v84, v84, v150, s[16:17]
	v_cndmask_b32_e64 v85, v85, v150, s[18:19]
	v_cndmask_b32_e64 v86, v86, v150, s[20:21]
	v_cndmask_b32_e64 v87, v87, v150, s[22:23]
	v_cndmask_b32_e64 v88, v88, v150, s[24:25]
	v_cndmask_b32_e64 v89, v89, v150, s[26:27]
	v_cndmask_b32_e64 v90, v90, v150, s[28:29]
	v_cndmask_b32_e64 v91, v91, v150, s[30:31]
	v_cndmask_b32_e64 v92, v92, v150, s[34:35]
	v_cndmask_b32_e64 v93, v93, v150, s[36:37]
	v_cndmask_b32_e64 v94, v94, v150, s[38:39]
	v_cndmask_b32_e64 v95, v95, v150, s[40:41]

.LBB0_3747:
	v_sub_f32_e32 v0, v80, v231
	v_exp_f32_e32 v9, v0
	v_sub_f32_e32 v0, v81, v231
	v_exp_f32_e32 v10, v0
	v_sub_f32_e32 v0, v82, v231
	v_exp_f32_e32 v4, v0
	v_sub_f32_e32 v0, v83, v231
	v_exp_f32_e32 v0, v0
	v_add_f32_e32 v5, v9, v10
	v_pk_add_f32 v[2:3], v[4:5], v[0:1]
	s_nop 0
	v_pk_add_f32 v[6:7], v[2:3], v[2:3] op_sel_hi:[0,1]
	v_sub_f32_e32 v2, v84, v231
	v_exp_f32_e32 v13, v2
	v_sub_f32_e32 v2, v85, v231
	v_exp_f32_e32 v14, v2
	v_sub_f32_e32 v2, v86, v231
	v_exp_f32_e32 v8, v2
	v_sub_f32_e32 v2, v87, v231
	v_exp_f32_e32 v6, v2
	v_cvt_pk_bf16_f32 v2, v9, v10
	v_add_f32_e32 v9, v13, v14
	v_cvt_pk_bf16_f32 v3, v4, v0
	v_pk_add_f32 v[4:5], v[8:9], v[6:7]
	v_sub_f32_e32 v0, v88, v231
	v_pk_add_f32 v[10:11], v[4:5], v[4:5] op_sel_hi:[0,1]
	v_sub_f32_e32 v4, v89, v231
	v_exp_f32_e32 v9, v4
	v_sub_f32_e32 v4, v90, v231
	v_exp_f32_e32 v0, v0
	v_exp_f32_e32 v12, v4
	v_sub_f32_e32 v4, v91, v231
	v_exp_f32_e32 v10, v4
	v_cvt_pk_bf16_f32 v4, v13, v14
	v_add_f32_e32 v13, v0, v9
	v_cvt_pk_bf16_f32 v5, v8, v6
	v_pk_add_f32 v[6:7], v[12:13], v[10:11]
	s_nop 0
	v_pk_add_f32 v[14:15], v[6:7], v[6:7] op_sel_hi:[0,1]
	v_sub_f32_e32 v6, v92, v231
	v_exp_f32_e32 v89, v6
	v_sub_f32_e32 v6, v93, v231
	v_exp_f32_e32 v90, v6
	v_sub_f32_e32 v6, v94, v231
	v_exp_f32_e32 v88, v6
	v_sub_f32_e32 v6, v95, v231
	v_exp_f32_e32 v14, v6
	v_cvt_pk_bf16_f32 v6, v0, v9
	v_cvt_pk_bf16_f32 v7, v12, v10
	v_cvt_pk_bf16_f32 v8, v89, v90
	v_cvt_pk_bf16_f32 v9, v88, v14
	ds_read_b64_tr_b16 v[10:11], v199
	ds_read_b64_tr_b16 v[12:13], v200
	ds_read_b64_tr_b16 v[80:81], v201
	ds_read_b64_tr_b16 v[82:83], v202
	ds_read_b64_tr_b16 v[84:85], v203
	ds_read_b64_tr_b16 v[86:87], v204
	v_add_f32_e32 v89, v89, v90
	v_pk_add_f32 v[14:15], v[88:89], v[14:15]
	s_nop 0
	v_add_f32_e32 v0, v14, v15
	v_add_f32_e32 v168, v168, v0
	s_setprio 1
	s_waitcnt lgkmcnt(4)
	v_mfma_f32_32x32x16_bf16 v[64:79], v[10:13], v[2:5], v[64:79]
	ds_read_b64_tr_b16 v[88:89], v226
	ds_read_b64_tr_b16 v[90:91], v205
	s_waitcnt lgkmcnt(4)
	v_mfma_f32_32x32x16_bf16 v[48:63], v[80:83], v[2:5], v[48:63]
	ds_read_b64_tr_b16 v[10:11], v206
	ds_read_b64_tr_b16 v[12:13], v227 offset:6144
	s_waitcnt lgkmcnt(4)
	v_mfma_f32_32x32x16_bf16 v[32:47], v[84:87], v[2:5], v[32:47]
	ds_read_b64_tr_b16 v[80:81], v207
	ds_read_b64_tr_b16 v[82:83], v228 offset:6144
	s_waitcnt lgkmcnt(4)
	v_mfma_f32_32x32x16_bf16 v[16:31], v[88:91], v[2:5], v[16:31]
	ds_read_b64_tr_b16 v[84:85], v208
	ds_read_b64_tr_b16 v[86:87], v229 offset:6144
	s_waitcnt lgkmcnt(4)
	v_mfma_f32_32x32x16_bf16 v[64:79], v[10:13], v[6:9], v[64:79]
	ds_read_b64_tr_b16 v[2:3], v209
	ds_read_b64_tr_b16 v[4:5], v230 offset:6144
	s_waitcnt lgkmcnt(4)
	v_mfma_f32_32x32x16_bf16 v[48:63], v[80:83], v[6:9], v[48:63]
	s_waitcnt lgkmcnt(2)
	v_mfma_f32_32x32x16_bf16 v[32:47], v[84:87], v[6:9], v[32:47]
	s_waitcnt lgkmcnt(0)
	v_mfma_f32_32x32x16_bf16 v[16:31], v[2:5], v[6:9], v[16:31]
	s_setprio 0
	s_cmp_gt_i32 s74, s46
	s_cbranch_scc1 .LBB0_3726
	v_add_u32_e32 v0, v167, v155
	v_add_u32_e32 v6, v167, v156
	ds_read_b128 v[2:5], v0 offset:24576
	ds_read_b128 v[6:9], v6 offset:24576
	v_add_u32_e32 v0, v167, v157
	v_add_u32_e32 v14, v167, v158
	ds_read_b128 v[10:13], v0 offset:24576
	ds_read_b128 v[232:235], v14 offset:24576
	s_setprio 1
	s_waitcnt lgkmcnt(3)
	v_mfma_f32_32x32x16_bf16 v[80:95], v[2:5], v[140:143], 0
	v_add_u32_e32 v0, v167, v159
	ds_read_b128 v[236:239], v0 offset:24576
	s_waitcnt lgkmcnt(3)
	v_mfma_f32_32x32x16_bf16 v[80:95], v[6:9], v[136:139], v[80:95]
	v_add_u32_e32 v0, v167, v160
	ds_read_b128 v[2:5], v0 offset:24576
	s_waitcnt lgkmcnt(3)
	v_mfma_f32_32x32x16_bf16 v[80:95], v[10:13], v[132:135], v[80:95]
	v_add_u32_e32 v0, v167, v161
	ds_read_b128 v[6:9], v0 offset:24576
	s_waitcnt lgkmcnt(3)
	v_mfma_f32_32x32x16_bf16 v[80:95], v[232:235], v[128:131], v[80:95]
	v_add_u32_e32 v0, v167, v162
	ds_read_b128 v[10:13], v0 offset:24576
	s_waitcnt lgkmcnt(3)
	v_mfma_f32_32x32x16_bf16 v[80:95], v[236:239], v[124:127], v[80:95]
	v_add_u32_e32 v0, v167, v163
	ds_read_b128 v[232:235], v0 offset:24576
	s_waitcnt lgkmcnt(3)
	v_mfma_f32_32x32x16_bf16 v[80:95], v[2:5], v[120:123], v[80:95]
	v_add_u32_e32 v0, v167, v164
	ds_read_b128 v[236:239], v0 offset:24576
	s_waitcnt lgkmcnt(3)
	v_mfma_f32_32x32x16_bf16 v[80:95], v[6:9], v[116:119], v[80:95]
	v_add_u32_e32 v0, v167, v165
	ds_read_b128 v[2:5], v0 offset:24576
	s_waitcnt lgkmcnt(3)
	v_mfma_f32_32x32x16_bf16 v[80:95], v[10:13], v[112:115], v[80:95]
	v_add_u32_e32 v0, v167, v166
	ds_read_b128 v[6:9], v0 offset:24576
	s_waitcnt lgkmcnt(3)
	v_mfma_f32_32x32x16_bf16 v[80:95], v[232:235], v[108:111], v[80:95]
	s_waitcnt lgkmcnt(2)
	v_mfma_f32_32x32x16_bf16 v[80:95], v[236:239], v[104:107], v[80:95]
	s_waitcnt lgkmcnt(1)
	v_mfma_f32_32x32x16_bf16 v[80:95], v[2:5], v[100:103], v[80:95]
	s_waitcnt lgkmcnt(0)
	v_mfma_f32_32x32x16_bf16 v[80:95], v[6:9], v[96:99], v[80:95]
	s_setprio 0
	s_cmp_lg_u32 s75, 0
	s_cbranch_scc1 .LBB0_3750
	s_nop 8
	v_cndmask_b32_e64 v0, v80, v150, s[8:9]
	v_cndmask_b32_e64 v81, v150, v81, s[10:11]
	v_cndmask_b32_e64 v80, v0, v80, s[10:11]
	v_cndmask_b32_e64 v82, v82, v150, s[12:13]
	v_cndmask_b32_e64 v83, v83, v150, s[14:15]
	v_cndmask_b32_e64 v84, v84, v150, s[16:17]
	v_cndmask_b32_e64 v85, v85, v150, s[18:19]
	v_cndmask_b32_e64 v86, v86, v150, s[20:21]
	v_cndmask_b32_e64 v87, v87, v150, s[22:23]
	v_cndmask_b32_e64 v88, v88, v150, s[24:25]
	v_cndmask_b32_e64 v89, v89, v150, s[26:27]
	v_cndmask_b32_e64 v90, v90, v150, s[28:29]
	v_cndmask_b32_e64 v91, v91, v150, s[30:31]
	v_cndmask_b32_e64 v92, v92, v150, s[34:35]
	v_cndmask_b32_e64 v93, v93, v150, s[36:37]
	v_cndmask_b32_e64 v94, v94, v150, s[38:39]
	v_cndmask_b32_e64 v95, v95, v150, s[40:41]

.LBB0_3783:
	v_sub_f32_e32 v0, v80, v233
	v_exp_f32_e32 v236, v0
	v_sub_f32_e32 v0, v81, v233
	v_exp_f32_e32 v237, v0
	v_sub_f32_e32 v0, v82, v233
	v_exp_f32_e32 v82, v0
	v_sub_f32_e32 v0, v83, v233
	v_exp_f32_e32 v0, v0
	v_add_f32_e32 v83, v236, v237
	v_pk_add_f32 v[80:81], v[82:83], v[0:1]
	s_nop 0
	v_pk_add_f32 v[234:235], v[80:81], v[80:81] op_sel_hi:[0,1]
	v_sub_f32_e32 v80, v84, v233
	v_exp_f32_e32 v238, v80
	v_sub_f32_e32 v80, v85, v233
	v_exp_f32_e32 v239, v80
	v_sub_f32_e32 v80, v86, v233
	v_exp_f32_e32 v84, v80
	v_sub_f32_e32 v80, v87, v233
	v_exp_f32_e32 v234, v80
	v_add_f32_e32 v85, v238, v239
	v_cvt_pk_bf16_f32 v80, v236, v237
	v_cvt_pk_bf16_f32 v81, v82, v0
	v_pk_add_f32 v[82:83], v[84:85], v[234:235]
	v_sub_f32_e32 v0, v88, v233
	v_pk_add_f32 v[86:87], v[82:83], v[82:83] op_sel_hi:[0,1]
	v_sub_f32_e32 v82, v89, v233
	v_exp_f32_e32 v235, v82
	v_sub_f32_e32 v82, v90, v233
	v_exp_f32_e32 v0, v0
	v_exp_f32_e32 v88, v82
	v_sub_f32_e32 v82, v91, v233
	v_exp_f32_e32 v86, v82
	v_add_f32_e32 v89, v0, v235
	v_cvt_pk_bf16_f32 v82, v238, v239
	v_cvt_pk_bf16_f32 v83, v84, v234
	v_pk_add_f32 v[84:85], v[88:89], v[86:87]
	s_nop 0
	v_pk_add_f32 v[238:239], v[84:85], v[84:85] op_sel_hi:[0,1]
	v_sub_f32_e32 v84, v92, v233
	v_exp_f32_e32 v241, v84
	v_sub_f32_e32 v84, v93, v233
	v_exp_f32_e32 v242, v84
	v_sub_f32_e32 v84, v94, v233
	v_exp_f32_e32 v240, v84
	v_sub_f32_e32 v84, v95, v233
	v_exp_f32_e32 v238, v84
	v_cvt_pk_bf16_f32 v84, v0, v235
	v_cvt_pk_bf16_f32 v85, v88, v86
	v_cvt_pk_bf16_f32 v86, v241, v242
	v_cvt_pk_bf16_f32 v87, v240, v238
	ds_read_b64_tr_b16 v[88:89], v179 offset:49152
	ds_read_b64_tr_b16 v[90:91], v180 offset:49152
	ds_read_b64_tr_b16 v[92:93], v181 offset:49152
	ds_read_b64_tr_b16 v[94:95], v182 offset:49152
	ds_read_b64_tr_b16 v[234:235], v183 offset:49152
	ds_read_b64_tr_b16 v[236:237], v184 offset:49152
	v_add_f32_e32 v241, v241, v242
	v_pk_add_f32 v[238:239], v[240:241], v[238:239]
	s_nop 0
	v_add_f32_e32 v0, v238, v239
	v_add_f32_e32 v178, v178, v0
	s_setprio 1
	s_waitcnt lgkmcnt(4)
	v_mfma_f32_32x32x16_bf16 v[64:79], v[88:91], v[80:83], v[64:79]
	ds_read_b64_tr_b16 v[238:239], v223 offset:49152
	ds_read_b64_tr_b16 v[240:241], v185 offset:49152
	s_waitcnt lgkmcnt(4)
	v_mfma_f32_32x32x16_bf16 v[48:63], v[92:95], v[80:83], v[48:63]
	ds_read_b64_tr_b16 v[88:89], v186 offset:49152
	ds_read_b64_tr_b16 v[90:91], v224 offset:55296
	s_waitcnt lgkmcnt(4)
	v_mfma_f32_32x32x16_bf16 v[32:47], v[234:237], v[80:83], v[32:47]
	ds_read_b64_tr_b16 v[92:93], v187 offset:49152
	ds_read_b64_tr_b16 v[94:95], v225 offset:55296
	s_waitcnt lgkmcnt(4)
	v_mfma_f32_32x32x16_bf16 v[16:31], v[238:241], v[80:83], v[16:31]
	ds_read_b64_tr_b16 v[234:235], v188 offset:49152
	ds_read_b64_tr_b16 v[236:237], v226 offset:55296
	s_waitcnt lgkmcnt(4)
	v_mfma_f32_32x32x16_bf16 v[64:79], v[88:91], v[84:87], v[64:79]
	ds_read_b64_tr_b16 v[80:81], v189 offset:49152
	ds_read_b64_tr_b16 v[82:83], v227 offset:55296
	s_waitcnt lgkmcnt(4)
	v_mfma_f32_32x32x16_bf16 v[48:63], v[92:95], v[84:87], v[48:63]
	s_waitcnt lgkmcnt(2)
	v_mfma_f32_32x32x16_bf16 v[32:47], v[234:237], v[84:87], v[32:47]
	s_waitcnt lgkmcnt(0)
	v_mfma_f32_32x32x16_bf16 v[16:31], v[80:83], v[84:87], v[16:31]
	s_setprio 0
	s_sub_i32 s4, s67, 64
	s_cmp_gt_i32 s4, s88
	s_cbranch_scc1 .LBB0_3789
	v_add_u32_e32 v0, v169, v157
	v_add_u32_e32 v84, v169, v158
	ds_read_b128 v[80:83], v0
	ds_read_b128 v[234:237], v84
	v_add_u32_e32 v0, v169, v159
	v_add_u32_e32 v84, v169, v160
	ds_read_b128 v[238:241], v0
	ds_read_b128 v[242:245], v84
	s_add_i32 s4, s89, s67
	s_setprio 1
	s_waitcnt lgkmcnt(3)
	v_mfma_f32_32x32x16_bf16 v[80:95], v[80:83], v[140:143], 0
	v_add_u32_e32 v0, v169, v161
	ds_read_b128 v[246:249], v0
	s_waitcnt lgkmcnt(3)
	v_mfma_f32_32x32x16_bf16 v[80:95], v[234:237], v[136:139], v[80:95]
	v_add_u32_e32 v0, v169, v162
	ds_read_b128 v[250:253], v0
	s_waitcnt lgkmcnt(3)
	v_mfma_f32_32x32x16_bf16 v[80:95], v[238:241], v[132:135], v[80:95]
	v_add_u32_e32 v0, v169, v163
	ds_read_b128 v[234:237], v0
	s_waitcnt lgkmcnt(3)
	v_mfma_f32_32x32x16_bf16 v[80:95], v[242:245], v[128:131], v[80:95]
	v_add_u32_e32 v0, v169, v164
	ds_read_b128 v[238:241], v0
	s_waitcnt lgkmcnt(3)
	v_mfma_f32_32x32x16_bf16 v[80:95], v[246:249], v[124:127], v[80:95]
	v_add_u32_e32 v0, v169, v165
	ds_read_b128 v[242:245], v0
	s_waitcnt lgkmcnt(3)
	v_mfma_f32_32x32x16_bf16 v[80:95], v[250:253], v[120:123], v[80:95]
	v_add_u32_e32 v0, v169, v166
	ds_read_b128 v[246:249], v0
	s_waitcnt lgkmcnt(3)
	v_mfma_f32_32x32x16_bf16 v[80:95], v[234:237], v[116:119], v[80:95]
	v_add_u32_e32 v0, v169, v167
	ds_read_b128 v[250:253], v0
	s_waitcnt lgkmcnt(3)
	v_mfma_f32_32x32x16_bf16 v[80:95], v[238:241], v[112:115], v[80:95]
	v_add_u32_e32 v0, v169, v168
	ds_read_b128 v[234:237], v0
	s_waitcnt lgkmcnt(3)
	v_mfma_f32_32x32x16_bf16 v[80:95], v[242:245], v[108:111], v[80:95]
	s_waitcnt lgkmcnt(2)
	v_mfma_f32_32x32x16_bf16 v[80:95], v[246:249], v[104:107], v[80:95]
	s_waitcnt lgkmcnt(1)
	v_mfma_f32_32x32x16_bf16 v[80:95], v[250:253], v[100:103], v[80:95]
	s_waitcnt lgkmcnt(0)
	v_mfma_f32_32x32x16_bf16 v[80:95], v[234:237], v[96:99], v[80:95]
	s_setprio 0
	s_cmpk_lg_i32 s4, 0x60
	s_cbranch_scc1 .LBB0_3786
	s_nop 8
	v_cndmask_b32_e64 v0, v80, v150, s[8:9]
	v_cndmask_b32_e64 v81, v150, v81, s[10:11]
	v_cndmask_b32_e64 v80, v0, v80, s[10:11]
	v_cndmask_b32_e64 v82, v82, v150, s[12:13]
	v_cndmask_b32_e64 v83, v83, v150, s[14:15]
	v_cndmask_b32_e64 v84, v84, v150, s[16:17]
	v_cndmask_b32_e64 v85, v85, v150, s[18:19]
	v_cndmask_b32_e64 v86, v86, v150, s[20:21]
	v_cndmask_b32_e64 v87, v87, v150, s[22:23]
	v_cndmask_b32_e64 v88, v88, v150, s[24:25]
	v_cndmask_b32_e64 v89, v89, v150, s[26:27]
	v_cndmask_b32_e64 v90, v90, v150, s[28:29]
	v_cndmask_b32_e64 v91, v91, v150, s[30:31]
	v_cndmask_b32_e64 v92, v92, v150, s[34:35]
	v_cndmask_b32_e64 v93, v93, v150, s[36:37]
	v_cndmask_b32_e64 v94, v94, v150, s[38:39]
	v_cndmask_b32_e64 v95, v95, v150, s[40:41]

.LBB0_3796:
	v_sub_f32_e32 v0, v80, v233
	v_exp_f32_e32 v9, v0
	v_sub_f32_e32 v0, v81, v233
	v_exp_f32_e32 v10, v0
	v_sub_f32_e32 v0, v82, v233
	v_exp_f32_e32 v4, v0
	v_sub_f32_e32 v0, v83, v233
	v_exp_f32_e32 v0, v0
	v_add_f32_e32 v5, v9, v10
	v_pk_add_f32 v[2:3], v[4:5], v[0:1]
	s_nop 0
	v_pk_add_f32 v[6:7], v[2:3], v[2:3] op_sel_hi:[0,1]
	v_sub_f32_e32 v2, v84, v233
	v_exp_f32_e32 v13, v2
	v_sub_f32_e32 v2, v85, v233
	v_exp_f32_e32 v14, v2
	v_sub_f32_e32 v2, v86, v233
	v_exp_f32_e32 v8, v2
	v_sub_f32_e32 v2, v87, v233
	v_exp_f32_e32 v6, v2
	v_cvt_pk_bf16_f32 v2, v9, v10
	v_add_f32_e32 v9, v13, v14
	v_cvt_pk_bf16_f32 v3, v4, v0
	v_pk_add_f32 v[4:5], v[8:9], v[6:7]
	v_sub_f32_e32 v0, v88, v233
	v_pk_add_f32 v[10:11], v[4:5], v[4:5] op_sel_hi:[0,1]
	v_sub_f32_e32 v4, v89, v233
	v_exp_f32_e32 v9, v4
	v_sub_f32_e32 v4, v90, v233
	v_exp_f32_e32 v0, v0
	v_exp_f32_e32 v12, v4
	v_sub_f32_e32 v4, v91, v233
	v_exp_f32_e32 v10, v4
	v_cvt_pk_bf16_f32 v4, v13, v14
	v_add_f32_e32 v13, v0, v9
	v_cvt_pk_bf16_f32 v5, v8, v6
	v_pk_add_f32 v[6:7], v[12:13], v[10:11]
	s_nop 0
	v_pk_add_f32 v[14:15], v[6:7], v[6:7] op_sel_hi:[0,1]
	v_sub_f32_e32 v6, v92, v233
	v_exp_f32_e32 v89, v6
	v_sub_f32_e32 v6, v93, v233
	v_exp_f32_e32 v90, v6
	v_sub_f32_e32 v6, v94, v233
	v_exp_f32_e32 v88, v6
	v_sub_f32_e32 v6, v95, v233
	v_exp_f32_e32 v14, v6
	v_cvt_pk_bf16_f32 v6, v0, v9
	v_cvt_pk_bf16_f32 v7, v12, v10
	v_cvt_pk_bf16_f32 v8, v89, v90
	v_cvt_pk_bf16_f32 v9, v88, v14
	ds_read_b64_tr_b16 v[10:11], v201
	ds_read_b64_tr_b16 v[12:13], v202
	ds_read_b64_tr_b16 v[80:81], v203
	ds_read_b64_tr_b16 v[82:83], v204
	ds_read_b64_tr_b16 v[84:85], v205
	ds_read_b64_tr_b16 v[86:87], v206
	v_add_f32_e32 v89, v89, v90
	v_pk_add_f32 v[14:15], v[88:89], v[14:15]
	s_nop 0
	v_add_f32_e32 v0, v14, v15
	v_add_f32_e32 v178, v178, v0
	s_setprio 1
	s_waitcnt lgkmcnt(4)
	v_mfma_f32_32x32x16_bf16 v[64:79], v[10:13], v[2:5], v[64:79]
	ds_read_b64_tr_b16 v[88:89], v228
	ds_read_b64_tr_b16 v[90:91], v207
	s_waitcnt lgkmcnt(4)
	v_mfma_f32_32x32x16_bf16 v[48:63], v[80:83], v[2:5], v[48:63]
	ds_read_b64_tr_b16 v[10:11], v208
	ds_read_b64_tr_b16 v[12:13], v229 offset:6144
	s_waitcnt lgkmcnt(4)
	v_mfma_f32_32x32x16_bf16 v[32:47], v[84:87], v[2:5], v[32:47]
	ds_read_b64_tr_b16 v[80:81], v209
	ds_read_b64_tr_b16 v[82:83], v230 offset:6144
	s_waitcnt lgkmcnt(4)
	v_mfma_f32_32x32x16_bf16 v[16:31], v[88:91], v[2:5], v[16:31]
	ds_read_b64_tr_b16 v[84:85], v210
	ds_read_b64_tr_b16 v[86:87], v231 offset:6144
	s_waitcnt lgkmcnt(4)
	v_mfma_f32_32x32x16_bf16 v[64:79], v[10:13], v[6:9], v[64:79]
	ds_read_b64_tr_b16 v[2:3], v211
	ds_read_b64_tr_b16 v[4:5], v232 offset:6144
	s_waitcnt lgkmcnt(4)
	v_mfma_f32_32x32x16_bf16 v[48:63], v[80:83], v[6:9], v[48:63]
	s_waitcnt lgkmcnt(2)
	v_mfma_f32_32x32x16_bf16 v[32:47], v[84:87], v[6:9], v[32:47]
	s_waitcnt lgkmcnt(0)
	v_mfma_f32_32x32x16_bf16 v[16:31], v[2:5], v[6:9], v[16:31]
	s_setprio 0
	s_cmp_gt_i32 s67, s88
	s_cbranch_scc1 .LBB0_3775
	v_add_u32_e32 v0, v169, v157
	v_add_u32_e32 v6, v169, v158
	ds_read_b128 v[2:5], v0 offset:24576
	ds_read_b128 v[6:9], v6 offset:24576
	v_add_u32_e32 v0, v169, v159
	v_add_u32_e32 v14, v169, v160
	ds_read_b128 v[10:13], v0 offset:24576
	ds_read_b128 v[234:237], v14 offset:24576
	s_setprio 1
	s_waitcnt lgkmcnt(3)
	v_mfma_f32_32x32x16_bf16 v[80:95], v[2:5], v[140:143], 0
	v_add_u32_e32 v0, v169, v161
	ds_read_b128 v[238:241], v0 offset:24576
	s_waitcnt lgkmcnt(3)
	v_mfma_f32_32x32x16_bf16 v[80:95], v[6:9], v[136:139], v[80:95]
	v_add_u32_e32 v0, v169, v162
	ds_read_b128 v[2:5], v0 offset:24576
	s_waitcnt lgkmcnt(3)
	v_mfma_f32_32x32x16_bf16 v[80:95], v[10:13], v[132:135], v[80:95]
	v_add_u32_e32 v0, v169, v163
	ds_read_b128 v[6:9], v0 offset:24576
	s_waitcnt lgkmcnt(3)
	v_mfma_f32_32x32x16_bf16 v[80:95], v[234:237], v[128:131], v[80:95]
	v_add_u32_e32 v0, v169, v164
	ds_read_b128 v[10:13], v0 offset:24576
	s_waitcnt lgkmcnt(3)
	v_mfma_f32_32x32x16_bf16 v[80:95], v[238:241], v[124:127], v[80:95]
	v_add_u32_e32 v0, v169, v165
	ds_read_b128 v[234:237], v0 offset:24576
	s_waitcnt lgkmcnt(3)
	v_mfma_f32_32x32x16_bf16 v[80:95], v[2:5], v[120:123], v[80:95]
	v_add_u32_e32 v0, v169, v166
	ds_read_b128 v[238:241], v0 offset:24576
	s_waitcnt lgkmcnt(3)
	v_mfma_f32_32x32x16_bf16 v[80:95], v[6:9], v[116:119], v[80:95]
	v_add_u32_e32 v0, v169, v167
	ds_read_b128 v[2:5], v0 offset:24576
	s_waitcnt lgkmcnt(3)
	v_mfma_f32_32x32x16_bf16 v[80:95], v[10:13], v[112:115], v[80:95]
	v_add_u32_e32 v0, v169, v168
	ds_read_b128 v[6:9], v0 offset:24576
	s_waitcnt lgkmcnt(3)
	v_mfma_f32_32x32x16_bf16 v[80:95], v[234:237], v[108:111], v[80:95]
	s_waitcnt lgkmcnt(2)
	v_mfma_f32_32x32x16_bf16 v[80:95], v[238:241], v[104:107], v[80:95]
	s_waitcnt lgkmcnt(1)
	v_mfma_f32_32x32x16_bf16 v[80:95], v[2:5], v[100:103], v[80:95]
	s_waitcnt lgkmcnt(0)
	v_mfma_f32_32x32x16_bf16 v[80:95], v[6:9], v[96:99], v[80:95]
	s_setprio 0
	s_cmp_lg_u32 s84, 0
	s_cbranch_scc1 .LBB0_3799
	s_nop 8
	v_cndmask_b32_e64 v0, v80, v150, s[8:9]
	v_cndmask_b32_e64 v81, v150, v81, s[10:11]
	v_cndmask_b32_e64 v80, v0, v80, s[10:11]
	v_cndmask_b32_e64 v82, v82, v150, s[12:13]
	v_cndmask_b32_e64 v83, v83, v150, s[14:15]
	v_cndmask_b32_e64 v84, v84, v150, s[16:17]
	v_cndmask_b32_e64 v85, v85, v150, s[18:19]
	v_cndmask_b32_e64 v86, v86, v150, s[20:21]
	v_cndmask_b32_e64 v87, v87, v150, s[22:23]
	v_cndmask_b32_e64 v88, v88, v150, s[24:25]
	v_cndmask_b32_e64 v89, v89, v150, s[26:27]
	v_cndmask_b32_e64 v90, v90, v150, s[28:29]
	v_cndmask_b32_e64 v91, v91, v150, s[30:31]
	v_cndmask_b32_e64 v92, v92, v150, s[34:35]
	v_cndmask_b32_e64 v93, v93, v150, s[36:37]
	v_cndmask_b32_e64 v94, v94, v150, s[38:39]
	v_cndmask_b32_e64 v95, v95, v150, s[40:41]
